# MFMA pairs grouped by shared B-fragment registers (variant of v026)
# speedup vs baseline: 1.0065x; 1.0004x over previous
; #define PG8_STAGE(bufoff, gbase, voff) do { _Pragma("unroll") for (int _i = 0; _i < 2; ++_i) \
;         __builtin_amdgcn_global_load_lds((const unsigned*)((const char*)(gbase) + (voff)[_i]), (LAS unsigned*)(lds + (bufoff) + ldsw + _i * 8192), 16, 0, 0); } while (0)
; #define PG8_LDA(dst, b, h) do { _Pragma("unroll") for (int m = 0; m < 4; ++m) _Pragma("unroll") for (int k = 0; k < 2; ++k) dst[m][k] = *(const LAS bf16x8*)(lds + PG8_SA(b, h) + aoff + m * 2048 + k * 1024); } while (0)
; #define PG8_LDB(dst, b, h) do { _Pragma("unroll") for (int n = 0; n < 2; ++n) _Pragma("unroll") for (int k = 0; k < 2; ++k) dst[n][k] = *(const LAS bf16x8*)(lds + PG8_SB(b, h) + boff + n * 2048 + k * 1024); } while (0)
; #define PG8_MMA(ai, bj, At, Bt) do { __builtin_amdgcn_s_setprio(1); _Pragma("unroll") for (int m = 0; m < 4; ++m) _Pragma("unroll") for (int n = 0; n < 2; ++n) _Pragma("unroll") for (int k = 0; k < 2; ++k) \
;         acc[ai][bj][m][n] = __builtin_amdgcn_mfma_f32_16x16x32_bf16(Bt[n][k], At[m][k], acc[ai][bj][m][n], 0, 0, 0); __builtin_amdgcn_s_setprio(0); } while (0)
; #define PG8_WAIT_V(n) asm volatile("s_waitcnt vmcnt(" #n ")" ::: "memory")
; #define PG8_WAIT_L(n) asm volatile("s_waitcnt lgkmcnt(" #n ")" ::: "memory")
; template <bool ALIGN_EPI, class Epi, class Sched>
; __device__ __forceinline__ void gemm_phase(LAS unsigned char* lds, const int lda, const int ldb, const int K, const Sched& S, const Epi& E, const size_t kstepA = (size_t)(BK * 2), const size_t kstepB = (size_t)(BK * 2)) {
;     ...
;         for (int t = 0; t < nt; t += 2) {
;             const bool last = (t == nt - 2);
;             const char* a1 = cA + (size_t)(t + 1) * kstepA;
;             const char* a2 = last ? nA : cA + (size_t)(t + 2) * kstepA; const char* b2 = last ? nB : cB + (size_t)(t + 2) * kstep;
;             const char* a3 = a2 + kstepA; const char* b3 = b2 + kstep;
;             PG8_LDB(B0, 0, 0); PG8_LDB(B1, 0, 1); PG8_SCHED; PG8_LDA(At, 0, 0); PG8_STAGE(PG8_SA(1, 1), a1 + hstepA, voffA);
;             PG8_WAIT_V(8); PG8_WAIT_L(0); PG8_BAR; PG8_MMA(0, 0, At, B0); PG8_MMA(0, 1, At, B1); PG8_BAR; PG8_SCHED;
;             PG8_LDA(At, 0, 1); PG8_STAGE(PG8_SB(0, 0), b2, voffB); PG8_STAGE(PG8_SB(0, 1), b2 + hstepB, voffB); PG8_STAGE(PG8_SA(0, 0), a2, voffA);
;             PG8_WAIT_V(8); PG8_WAIT_L(0); PG8_BAR; PG8_MMA(1, 0, At, B0); PG8_MMA(1, 1, At, B1); PG8_BAR; PG8_SCHED;
.LBB0_139:
	ds_read_b128 v[154:157], v150
	ds_read_b128 v[158:161], v150 offset:1024
	ds_read_b128 v[162:165], v150 offset:2048
	ds_read_b128 v[166:169], v150 offset:3072
	ds_read_b128 v[170:173], v151
	ds_read_b128 v[174:177], v151 offset:1024
	ds_read_b128 v[178:181], v151 offset:2048
	ds_read_b128 v[194:197], v151 offset:3072
	s_add_u32 s54, s70, 0x1fc000
	s_addc_u32 s55, s71, 0
	s_cmp_eq_u32 s51, 28
	s_cselect_b32 s78, s6, s54
	s_cselect_b32 s79, s7, s55
	s_cselect_b32 s76, s68, s41
	s_cselect_b32 s77, s69, s49
	s_add_u32 s74, s78, 0x200000
	s_addc_u32 s75, s79, 0
	s_add_i32 m0, s20, 0xc000
	ds_read_b128 v[198:201], v152
	ds_read_b128 v[202:205], v152 offset:1024
	ds_read_b128 v[206:209], v152 offset:2048
	ds_read_b128 v[210:213], v152 offset:3072
	ds_read_b128 v[214:217], v152 offset:4096
	ds_read_b128 v[218:221], v152 offset:5120
	ds_read_b128 v[222:225], v152 offset:6144
	ds_read_b128 v[226:229], v152 offset:7168
	global_load_lds_dwordx4 v138, s[70:71]
	s_add_i32 m0, s20, 0xe000
	s_nop 0
	global_load_lds_dwordx4 v140, s[70:71]
	s_waitcnt vmcnt(8)
	s_waitcnt lgkmcnt(0)
	s_barrier
	s_waitcnt lgkmcnt(0)
	v_mfma_f32_16x16x32_bf16 v[124:127], v[154:157], v[198:201], v[124:127]
	v_mfma_f32_16x16x32_bf16 v[124:127], v[158:161], v[202:205], v[124:127]
	v_mfma_f32_16x16x32_bf16 v[108:111], v[154:157], v[206:209], v[108:111]
	v_mfma_f32_16x16x32_bf16 v[108:111], v[158:161], v[210:213], v[108:111]
	v_mfma_f32_16x16x32_bf16 v[92:95], v[154:157], v[214:217], v[92:95]
	v_mfma_f32_16x16x32_bf16 v[92:95], v[158:161], v[218:221], v[92:95]
	v_mfma_f32_16x16x32_bf16 v[76:79], v[154:157], v[222:225], v[76:79]
	v_mfma_f32_16x16x32_bf16 v[76:79], v[158:161], v[226:229], v[76:79]
	v_mfma_f32_16x16x32_bf16 v[116:119], v[162:165], v[198:201], v[116:119]
	v_mfma_f32_16x16x32_bf16 v[116:119], v[166:169], v[202:205], v[116:119]
	v_mfma_f32_16x16x32_bf16 v[100:103], v[162:165], v[206:209], v[100:103]
	v_mfma_f32_16x16x32_bf16 v[100:103], v[166:169], v[210:213], v[100:103]
	v_mfma_f32_16x16x32_bf16 v[84:87], v[162:165], v[214:217], v[84:87]
	v_mfma_f32_16x16x32_bf16 v[84:87], v[166:169], v[218:221], v[84:87]
	v_mfma_f32_16x16x32_bf16 v[68:71], v[162:165], v[222:225], v[68:71]
	v_mfma_f32_16x16x32_bf16 v[68:71], v[166:169], v[226:229], v[68:71]
	v_mfma_f32_16x16x32_bf16 v[120:123], v[170:173], v[198:201], v[120:123]
	v_mfma_f32_16x16x32_bf16 v[120:123], v[174:177], v[202:205], v[120:123]
	v_mfma_f32_16x16x32_bf16 v[104:107], v[170:173], v[206:209], v[104:107]
	v_mfma_f32_16x16x32_bf16 v[104:107], v[174:177], v[210:213], v[104:107]
	v_mfma_f32_16x16x32_bf16 v[88:91], v[170:173], v[214:217], v[88:91]
	v_mfma_f32_16x16x32_bf16 v[88:91], v[174:177], v[218:221], v[88:91]
	v_mfma_f32_16x16x32_bf16 v[72:75], v[170:173], v[222:225], v[72:75]
	v_mfma_f32_16x16x32_bf16 v[72:75], v[174:177], v[226:229], v[72:75]
	v_mfma_f32_16x16x32_bf16 v[112:115], v[178:181], v[198:201], v[112:115]
	v_mfma_f32_16x16x32_bf16 v[112:115], v[194:197], v[202:205], v[112:115]
	v_mfma_f32_16x16x32_bf16 v[96:99], v[178:181], v[206:209], v[96:99]
	v_mfma_f32_16x16x32_bf16 v[96:99], v[194:197], v[210:213], v[96:99]
	v_mfma_f32_16x16x32_bf16 v[80:83], v[178:181], v[214:217], v[80:83]
	v_mfma_f32_16x16x32_bf16 v[80:83], v[194:197], v[218:221], v[80:83]
	v_mfma_f32_16x16x32_bf16 v[64:67], v[178:181], v[222:225], v[64:67]
	v_mfma_f32_16x16x32_bf16 v[64:67], v[194:197], v[226:229], v[64:67]
	s_barrier
	s_add_i32 s54, s42, s18
	s_mov_b32 m0, s54
	ds_read_b128 v[198:201], v152 offset:16384
	ds_read_b128 v[202:205], v152 offset:17408
	ds_read_b128 v[206:209], v152 offset:18432
	ds_read_b128 v[210:213], v152 offset:19456
	ds_read_b128 v[214:217], v152 offset:20480
	ds_read_b128 v[218:221], v152 offset:21504
	ds_read_b128 v[222:225], v152 offset:22528
	ds_read_b128 v[226:229], v152 offset:23552
	global_load_lds_dwordx4 v132, s[76:77]
	s_add_i32 m0, s54, 0x2000
	s_add_u32 s54, s76, 0x4000
	s_addc_u32 s55, s77, 0
	s_add_i32 s56, s43, s18
	global_load_lds_dwordx4 v128, s[76:77]
	s_mov_b32 m0, s56
	s_nop 0
	global_load_lds_dwordx4 v132, s[54:55]
	s_add_i32 m0, s56, 0x2000
	s_nop 0
	global_load_lds_dwordx4 v128, s[54:55]
	s_mov_b32 m0, s20
	s_nop 0
	global_load_lds_dwordx4 v134, s[78:79]
	s_mov_b32 m0, s21
	s_nop 0
	global_load_lds_dwordx4 v130, s[78:79]
	s_waitcnt vmcnt(8)
	s_waitcnt lgkmcnt(0)
	s_barrier
	s_waitcnt lgkmcnt(0)
	v_mfma_f32_16x16x32_bf16 v[60:63], v[154:157], v[198:201], v[60:63]
	v_mfma_f32_16x16x32_bf16 v[60:63], v[158:161], v[202:205], v[60:63]
	v_mfma_f32_16x16x32_bf16 v[44:47], v[154:157], v[206:209], v[44:47]
	v_mfma_f32_16x16x32_bf16 v[44:47], v[158:161], v[210:213], v[44:47]
	v_mfma_f32_16x16x32_bf16 v[28:31], v[154:157], v[214:217], v[28:31]
	v_mfma_f32_16x16x32_bf16 v[28:31], v[158:161], v[218:221], v[28:31]
	v_mfma_f32_16x16x32_bf16 v[12:15], v[154:157], v[222:225], v[12:15]
	v_mfma_f32_16x16x32_bf16 v[12:15], v[158:161], v[226:229], v[12:15]
	v_mfma_f32_16x16x32_bf16 v[52:55], v[162:165], v[198:201], v[52:55]
	v_mfma_f32_16x16x32_bf16 v[52:55], v[166:169], v[202:205], v[52:55]
	v_mfma_f32_16x16x32_bf16 v[36:39], v[162:165], v[206:209], v[36:39]
	v_mfma_f32_16x16x32_bf16 v[36:39], v[166:169], v[210:213], v[36:39]
	v_mfma_f32_16x16x32_bf16 v[20:23], v[162:165], v[214:217], v[20:23]
	v_mfma_f32_16x16x32_bf16 v[20:23], v[166:169], v[218:221], v[20:23]
	v_mfma_f32_16x16x32_bf16 v[4:7], v[162:165], v[222:225], v[4:7]
	v_mfma_f32_16x16x32_bf16 v[4:7], v[166:169], v[226:229], v[4:7]
	v_mfma_f32_16x16x32_bf16 v[56:59], v[170:173], v[198:201], v[56:59]
	v_mfma_f32_16x16x32_bf16 v[56:59], v[174:177], v[202:205], v[56:59]
	v_mfma_f32_16x16x32_bf16 v[40:43], v[170:173], v[206:209], v[40:43]
	v_mfma_f32_16x16x32_bf16 v[40:43], v[174:177], v[210:213], v[40:43]
	v_mfma_f32_16x16x32_bf16 v[24:27], v[170:173], v[214:217], v[24:27]
	v_mfma_f32_16x16x32_bf16 v[24:27], v[174:177], v[218:221], v[24:27]
	v_mfma_f32_16x16x32_bf16 v[8:11], v[170:173], v[222:225], v[8:11]
	v_mfma_f32_16x16x32_bf16 v[8:11], v[174:177], v[226:229], v[8:11]
	v_mfma_f32_16x16x32_bf16 v[48:51], v[178:181], v[198:201], v[48:51]
	v_mfma_f32_16x16x32_bf16 v[48:51], v[194:197], v[202:205], v[48:51]
	v_mfma_f32_16x16x32_bf16 v[32:35], v[178:181], v[206:209], v[32:35]
	v_mfma_f32_16x16x32_bf16 v[32:35], v[194:197], v[210:213], v[32:35]
	v_mfma_f32_16x16x32_bf16 v[16:19], v[178:181], v[214:217], v[16:19]
	v_mfma_f32_16x16x32_bf16 v[16:19], v[194:197], v[218:221], v[16:19]
	v_mfma_f32_16x16x32_bf16 v[0:3], v[178:181], v[222:225], v[0:3]
	v_mfma_f32_16x16x32_bf16 v[0:3], v[194:197], v[226:229], v[0:3]
	s_barrier
; #define PG8_STAGE(bufoff, gbase, voff) do { _Pragma("unroll") for (int _i = 0; _i < 2; ++_i) \
;         __builtin_amdgcn_global_load_lds((const unsigned*)((const char*)(gbase) + (voff)[_i]), (LAS unsigned*)(lds + (bufoff) + ldsw + _i * 8192), 16, 0, 0); } while (0)
; #define PG8_LDA(dst, b, h) do { _Pragma("unroll") for (int m = 0; m < 4; ++m) _Pragma("unroll") for (int k = 0; k < 2; ++k) dst[m][k] = *(const LAS bf16x8*)(lds + PG8_SA(b, h) + aoff + m * 2048 + k * 1024); } while (0)
; #define PG8_LDB(dst, b, h) do { _Pragma("unroll") for (int n = 0; n < 2; ++n) _Pragma("unroll") for (int k = 0; k < 2; ++k) dst[n][k] = *(const LAS bf16x8*)(lds + PG8_SB(b, h) + boff + n * 2048 + k * 1024); } while (0)
; #define PG8_MMA(ai, bj, At, Bt) do { __builtin_amdgcn_s_setprio(1); _Pragma("unroll") for (int m = 0; m < 4; ++m) _Pragma("unroll") for (int n = 0; n < 2; ++n) _Pragma("unroll") for (int k = 0; k < 2; ++k) \
;         acc[ai][bj][m][n] = __builtin_amdgcn_mfma_f32_16x16x32_bf16(Bt[n][k], At[m][k], acc[ai][bj][m][n], 0, 0, 0); __builtin_amdgcn_s_setprio(0); } while (0)
; #define PG8_WAIT_V(n) asm volatile("s_waitcnt vmcnt(" #n ")" ::: "memory")
; #define PG8_WAIT_L(n) asm volatile("s_waitcnt lgkmcnt(" #n ")" ::: "memory")
; #define PG8_BAR __builtin_amdgcn_s_barrier()
; #define PG8_SCHED __builtin_amdgcn_sched_barrier(0)
; template <bool ALIGN_EPI, class Epi, class Sched>
; __device__ __forceinline__ void gemm_phase(LAS unsigned char* lds, const int lda, const int ldb, const int K, const Sched& S, const Epi& E, const size_t kstepA = (size_t)(BK * 2), const size_t kstepB = (size_t)(BK * 2)) {
;     ...
;             PG8_LDB(B0, 1, 0); PG8_LDB(B1, 1, 1); PG8_SCHED; PG8_LDA(At, 1, 0); PG8_STAGE(PG8_SA(0, 1), a2 + hstepA, voffA);
;             PG8_WAIT_V(8); PG8_WAIT_L(0); PG8_BAR; PG8_MMA(0, 0, At, B0); PG8_MMA(0, 1, At, B1); PG8_BAR; PG8_SCHED;
;             PG8_LDA(At, 1, 1); PG8_STAGE(PG8_SB(1, 0), b3, voffB); PG8_STAGE(PG8_SB(1, 1), b3 + hstepB, voffB); PG8_STAGE(PG8_SA(1, 0), a3, voffA);
;             PG8_WAIT_V(8); PG8_WAIT_L(0); PG8_BAR; PG8_MMA(1, 0, At, B0); PG8_MMA(1, 1, At, B1); PG8_BAR; PG8_SCHED;
;         }
	s_add_i32 s56, 0, 0x18000
	v_add_u32_e32 v146, s56, v149
	s_add_i32 s57, 0, 0x1c000
	ds_read_b128 v[154:157], v146
	ds_read_b128 v[158:161], v146 offset:1024
	ds_read_b128 v[162:165], v146 offset:2048
	ds_read_b128 v[166:169], v146 offset:3072
	v_add_u32_e32 v146, s57, v149
	ds_read_b128 v[170:173], v146
	ds_read_b128 v[174:177], v146 offset:1024
	ds_read_b128 v[178:181], v146 offset:2048
	ds_read_b128 v[194:197], v146 offset:3072
	s_add_u32 s54, s78, 0x4000
	s_addc_u32 s55, s79, 0
	s_mov_b32 m0, s22
	ds_read_b128 v[198:201], v152 offset:32768
	ds_read_b128 v[202:205], v152 offset:33792
	ds_read_b128 v[206:209], v152 offset:34816
	ds_read_b128 v[210:213], v152 offset:35840
	ds_read_b128 v[214:217], v152 offset:36864
	ds_read_b128 v[218:221], v152 offset:37888
	ds_read_b128 v[222:225], v152 offset:38912
	ds_read_b128 v[226:229], v152 offset:39936
	global_load_lds_dwordx4 v134, s[54:55]
	s_mov_b32 m0, s23
	s_nop 0
	global_load_lds_dwordx4 v130, s[54:55]
	s_waitcnt vmcnt(8)
	s_waitcnt lgkmcnt(0)
	s_barrier
	s_waitcnt lgkmcnt(0)
	v_mfma_f32_16x16x32_bf16 v[124:127], v[154:157], v[198:201], v[124:127]
	v_mfma_f32_16x16x32_bf16 v[124:127], v[158:161], v[202:205], v[124:127]
	v_mfma_f32_16x16x32_bf16 v[108:111], v[154:157], v[206:209], v[108:111]
	v_mfma_f32_16x16x32_bf16 v[108:111], v[158:161], v[210:213], v[108:111]
	v_mfma_f32_16x16x32_bf16 v[92:95], v[154:157], v[214:217], v[92:95]
	v_mfma_f32_16x16x32_bf16 v[92:95], v[158:161], v[218:221], v[92:95]
	v_mfma_f32_16x16x32_bf16 v[76:79], v[154:157], v[222:225], v[76:79]
	v_mfma_f32_16x16x32_bf16 v[76:79], v[158:161], v[226:229], v[76:79]
	v_mfma_f32_16x16x32_bf16 v[116:119], v[162:165], v[198:201], v[116:119]
	v_mfma_f32_16x16x32_bf16 v[116:119], v[166:169], v[202:205], v[116:119]
	v_mfma_f32_16x16x32_bf16 v[100:103], v[162:165], v[206:209], v[100:103]
	v_mfma_f32_16x16x32_bf16 v[100:103], v[166:169], v[210:213], v[100:103]
	v_mfma_f32_16x16x32_bf16 v[84:87], v[162:165], v[214:217], v[84:87]
	v_mfma_f32_16x16x32_bf16 v[84:87], v[166:169], v[218:221], v[84:87]
	v_mfma_f32_16x16x32_bf16 v[68:71], v[162:165], v[222:225], v[68:71]
	v_mfma_f32_16x16x32_bf16 v[68:71], v[166:169], v[226:229], v[68:71]
	v_mfma_f32_16x16x32_bf16 v[120:123], v[170:173], v[198:201], v[120:123]
	v_mfma_f32_16x16x32_bf16 v[120:123], v[174:177], v[202:205], v[120:123]
	v_mfma_f32_16x16x32_bf16 v[104:107], v[170:173], v[206:209], v[104:107]
	v_mfma_f32_16x16x32_bf16 v[104:107], v[174:177], v[210:213], v[104:107]
	v_mfma_f32_16x16x32_bf16 v[88:91], v[170:173], v[214:217], v[88:91]
	v_mfma_f32_16x16x32_bf16 v[88:91], v[174:177], v[218:221], v[88:91]
	v_mfma_f32_16x16x32_bf16 v[72:75], v[170:173], v[222:225], v[72:75]
	v_mfma_f32_16x16x32_bf16 v[72:75], v[174:177], v[226:229], v[72:75]
	v_mfma_f32_16x16x32_bf16 v[112:115], v[178:181], v[198:201], v[112:115]
	v_mfma_f32_16x16x32_bf16 v[112:115], v[194:197], v[202:205], v[112:115]
	v_mfma_f32_16x16x32_bf16 v[96:99], v[178:181], v[206:209], v[96:99]
	v_mfma_f32_16x16x32_bf16 v[96:99], v[194:197], v[210:213], v[96:99]
	v_mfma_f32_16x16x32_bf16 v[80:83], v[178:181], v[214:217], v[80:83]
	v_mfma_f32_16x16x32_bf16 v[80:83], v[194:197], v[218:221], v[80:83]
	v_mfma_f32_16x16x32_bf16 v[64:67], v[178:181], v[222:225], v[64:67]
	v_mfma_f32_16x16x32_bf16 v[64:67], v[194:197], v[226:229], v[64:67]
	s_barrier
	s_add_u32 s54, s76, 0x160000
	s_addc_u32 s55, s77, 0
	s_add_i32 s56, s56, s18
	s_mov_b32 m0, s56
	ds_read_b128 v[198:201], v152 offset:49152
	ds_read_b128 v[202:205], v152 offset:50176
	ds_read_b128 v[206:209], v152 offset:51200
	ds_read_b128 v[210:213], v152 offset:52224
	ds_read_b128 v[214:217], v152 offset:53248
	ds_read_b128 v[218:221], v152 offset:54272
	ds_read_b128 v[222:225], v152 offset:55296
	ds_read_b128 v[226:229], v152 offset:56320
	global_load_lds_dwordx4 v132, s[54:55]
	s_add_i32 m0, s56, 0x2000
	s_nop 0
	global_load_lds_dwordx4 v128, s[54:55]
	s_add_u32 s54, s76, 0x164000
	s_addc_u32 s55, s77, 0
	s_add_i32 s56, s57, s18
	s_mov_b32 m0, s56
	s_nop 0
	global_load_lds_dwordx4 v132, s[54:55]
	s_add_i32 m0, s56, 0x2000
	s_nop 0
	global_load_lds_dwordx4 v128, s[54:55]
	s_mov_b32 m0, s31
	s_nop 0
	global_load_lds_dwordx4 v134, s[74:75]
	s_mov_b32 m0, s33
	s_nop 0
	global_load_lds_dwordx4 v130, s[74:75]
	s_waitcnt vmcnt(8)
	s_waitcnt lgkmcnt(0)
	s_barrier
	s_waitcnt lgkmcnt(0)
	v_mfma_f32_16x16x32_bf16 v[60:63], v[154:157], v[198:201], v[60:63]
	v_mfma_f32_16x16x32_bf16 v[60:63], v[158:161], v[202:205], v[60:63]
	v_mfma_f32_16x16x32_bf16 v[44:47], v[154:157], v[206:209], v[44:47]
	v_mfma_f32_16x16x32_bf16 v[44:47], v[158:161], v[210:213], v[44:47]
	v_mfma_f32_16x16x32_bf16 v[28:31], v[154:157], v[214:217], v[28:31]
	v_mfma_f32_16x16x32_bf16 v[28:31], v[158:161], v[218:221], v[28:31]
	v_mfma_f32_16x16x32_bf16 v[12:15], v[154:157], v[222:225], v[12:15]
	v_mfma_f32_16x16x32_bf16 v[12:15], v[158:161], v[226:229], v[12:15]
	v_mfma_f32_16x16x32_bf16 v[52:55], v[162:165], v[198:201], v[52:55]
	v_mfma_f32_16x16x32_bf16 v[52:55], v[166:169], v[202:205], v[52:55]
	v_mfma_f32_16x16x32_bf16 v[36:39], v[162:165], v[206:209], v[36:39]
	v_mfma_f32_16x16x32_bf16 v[36:39], v[166:169], v[210:213], v[36:39]
	v_mfma_f32_16x16x32_bf16 v[20:23], v[162:165], v[214:217], v[20:23]
	v_mfma_f32_16x16x32_bf16 v[20:23], v[166:169], v[218:221], v[20:23]
	v_mfma_f32_16x16x32_bf16 v[4:7], v[162:165], v[222:225], v[4:7]
	v_mfma_f32_16x16x32_bf16 v[4:7], v[166:169], v[226:229], v[4:7]
	v_mfma_f32_16x16x32_bf16 v[56:59], v[170:173], v[198:201], v[56:59]
	v_mfma_f32_16x16x32_bf16 v[56:59], v[174:177], v[202:205], v[56:59]
	v_mfma_f32_16x16x32_bf16 v[40:43], v[170:173], v[206:209], v[40:43]
	v_mfma_f32_16x16x32_bf16 v[40:43], v[174:177], v[210:213], v[40:43]
	v_mfma_f32_16x16x32_bf16 v[24:27], v[170:173], v[214:217], v[24:27]
	v_mfma_f32_16x16x32_bf16 v[24:27], v[174:177], v[218:221], v[24:27]
	v_mfma_f32_16x16x32_bf16 v[8:11], v[170:173], v[222:225], v[8:11]
	v_mfma_f32_16x16x32_bf16 v[8:11], v[174:177], v[226:229], v[8:11]
	v_mfma_f32_16x16x32_bf16 v[48:51], v[178:181], v[198:201], v[48:51]
	v_mfma_f32_16x16x32_bf16 v[48:51], v[194:197], v[202:205], v[48:51]
	v_mfma_f32_16x16x32_bf16 v[32:35], v[178:181], v[206:209], v[32:35]
	v_mfma_f32_16x16x32_bf16 v[32:35], v[194:197], v[210:213], v[32:35]
	v_mfma_f32_16x16x32_bf16 v[16:19], v[178:181], v[214:217], v[16:19]
	v_mfma_f32_16x16x32_bf16 v[16:19], v[194:197], v[218:221], v[16:19]
	v_mfma_f32_16x16x32_bf16 v[0:3], v[178:181], v[222:225], v[0:3]
	v_mfma_f32_16x16x32_bf16 v[0:3], v[194:197], v[226:229], v[0:3]
	s_barrier
	s_add_i32 s51, s51, 2
	s_add_u32 s41, s41, 0x2c0000
	s_addc_u32 s49, s49, 0
	s_add_u32 s70, s70, 0x400000
	s_addc_u32 s71, s71, 0
	s_cmp_gt_u32 s51, 29
	s_cbranch_scc0 .LBB0_139
	s_and_b64 vcc, exec, s[12:13]
	s_cbranch_vccz .LBB0_142
	s_barrier

; #define PG8_STAGE(bufoff, gbase, voff) do { _Pragma("unroll") for (int _i = 0; _i < 2; ++_i) \
;         __builtin_amdgcn_global_load_lds((const unsigned*)((const char*)(gbase) + (voff)[_i]), (LAS unsigned*)(lds + (bufoff) + ldsw + _i * 8192), 16, 0, 0); } while (0)
; #define PG8_LDA(dst, b, h) do { _Pragma("unroll") for (int m = 0; m < 4; ++m) _Pragma("unroll") for (int k = 0; k < 2; ++k) dst[m][k] = *(const LAS bf16x8*)(lds + PG8_SA(b, h) + aoff + m * 2048 + k * 1024); } while (0)
; #define PG8_LDB(dst, b, h) do { _Pragma("unroll") for (int n = 0; n < 2; ++n) _Pragma("unroll") for (int k = 0; k < 2; ++k) dst[n][k] = *(const LAS bf16x8*)(lds + PG8_SB(b, h) + boff + n * 2048 + k * 1024); } while (0)
; #define PG8_MMA(ai, bj, At, Bt) do { __builtin_amdgcn_s_setprio(1); _Pragma("unroll") for (int m = 0; m < 4; ++m) _Pragma("unroll") for (int n = 0; n < 2; ++n) _Pragma("unroll") for (int k = 0; k < 2; ++k) \
;         acc[ai][bj][m][n] = __builtin_amdgcn_mfma_f32_16x16x32_bf16(Bt[n][k], At[m][k], acc[ai][bj][m][n], 0, 0, 0); __builtin_amdgcn_s_setprio(0); } while (0)
; #define PG8_WAIT_V(n) asm volatile("s_waitcnt vmcnt(" #n ")" ::: "memory")
; #define PG8_WAIT_L(n) asm volatile("s_waitcnt lgkmcnt(" #n ")" ::: "memory")
; template <bool ALIGN_EPI, class Epi, class Sched>
; __device__ __forceinline__ void gemm_phase(LAS unsigned char* lds, const int lda, const int ldb, const int K, const Sched& S, const Epi& E, const size_t kstepA = (size_t)(BK * 2), const size_t kstepB = (size_t)(BK * 2)) {
;     ...
;         for (int t = 0; t < nt; t += 2) {
;             const bool last = (t == nt - 2);
;             const char* a1 = cA + (size_t)(t + 1) * kstepA;
;             const char* a2 = last ? nA : cA + (size_t)(t + 2) * kstepA; const char* b2 = last ? nB : cB + (size_t)(t + 2) * kstep;
;             const char* a3 = a2 + kstepA; const char* b3 = b2 + kstep;
;             PG8_LDB(B0, 0, 0); PG8_LDB(B1, 0, 1); PG8_SCHED; PG8_LDA(At, 0, 0); PG8_STAGE(PG8_SA(1, 1), a1 + hstepA, voffA);
;             PG8_WAIT_V(8); PG8_WAIT_L(0); PG8_BAR; PG8_MMA(0, 0, At, B0); PG8_MMA(0, 1, At, B1); PG8_BAR; PG8_SCHED;
;             PG8_LDA(At, 0, 1); PG8_STAGE(PG8_SB(0, 0), b2, voffB); PG8_STAGE(PG8_SB(0, 1), b2 + hstepB, voffB); PG8_STAGE(PG8_SA(0, 0), a2, voffA);
;             PG8_WAIT_V(8); PG8_WAIT_L(0); PG8_BAR; PG8_MMA(1, 0, At, B0); PG8_MMA(1, 1, At, B1); PG8_BAR; PG8_SCHED;
.LBB0_218:
	ds_read_b128 v[64:67], v193
	ds_read_b128 v[68:71], v193 offset:1024
	ds_read_b128 v[80:83], v193 offset:2048
	ds_read_b128 v[84:87], v193 offset:3072
	ds_read_b128 v[144:147], v232
	ds_read_b128 v[148:151], v232 offset:1024
	ds_read_b128 v[152:155], v232 offset:2048
	ds_read_b128 v[156:159], v232 offset:3072
	s_add_u32 s54, s82, 0x1fc000
	s_addc_u32 s55, s83, 0
	s_cmpk_eq_i32 s51, 0x54
	s_cselect_b32 vcc_lo, s6, s54
	s_cselect_b32 vcc_hi, s7, s55
	s_cselect_b32 s96, s78, s13
	s_cselect_b32 s97, s79, s50
	s_add_u32 s94, vcc_lo, 0x200000
	s_addc_u32 s95, vcc_hi, 0
	s_add_i32 m0, s19, 0xc000
	ds_read_b128 v[160:163], v233
	ds_read_b128 v[164:167], v233 offset:1024
	ds_read_b128 v[168:171], v233 offset:2048
	ds_read_b128 v[172:175], v233 offset:3072
	ds_read_b128 v[176:179], v233 offset:4096
	ds_read_b128 v[180:183], v233 offset:5120
	ds_read_b128 v[212:215], v233 offset:6144
	ds_read_b128 v[216:219], v233 offset:7168
	global_load_lds_dwordx4 v204, s[82:83]
	s_add_i32 m0, s19, 0xe000
	s_nop 0
	global_load_lds_dwordx4 v206, s[82:83]
	s_waitcnt vmcnt(8)
	s_waitcnt lgkmcnt(0)
	s_barrier
	s_waitcnt lgkmcnt(0)
	v_mfma_f32_16x16x32_bf16 v[140:143], v[64:67], v[160:163], v[140:143]
	v_mfma_f32_16x16x32_bf16 v[140:143], v[68:71], v[164:167], v[140:143]
	v_mfma_f32_16x16x32_bf16 v[124:127], v[64:67], v[168:171], v[124:127]
	v_mfma_f32_16x16x32_bf16 v[124:127], v[68:71], v[172:175], v[124:127]
	v_mfma_f32_16x16x32_bf16 v[108:111], v[64:67], v[176:179], v[108:111]
	v_mfma_f32_16x16x32_bf16 v[108:111], v[68:71], v[180:183], v[108:111]
	v_mfma_f32_16x16x32_bf16 v[92:95], v[64:67], v[212:215], v[92:95]
	v_mfma_f32_16x16x32_bf16 v[92:95], v[68:71], v[216:219], v[92:95]
	v_mfma_f32_16x16x32_bf16 v[136:139], v[80:83], v[160:163], v[136:139]
	v_mfma_f32_16x16x32_bf16 v[136:139], v[84:87], v[164:167], v[136:139]
	v_mfma_f32_16x16x32_bf16 v[120:123], v[80:83], v[168:171], v[120:123]
	v_mfma_f32_16x16x32_bf16 v[120:123], v[84:87], v[172:175], v[120:123]
	v_mfma_f32_16x16x32_bf16 v[104:107], v[80:83], v[176:179], v[104:107]
	v_mfma_f32_16x16x32_bf16 v[104:107], v[84:87], v[180:183], v[104:107]
	v_mfma_f32_16x16x32_bf16 v[88:91], v[80:83], v[212:215], v[88:91]
	v_mfma_f32_16x16x32_bf16 v[88:91], v[84:87], v[216:219], v[88:91]
	v_mfma_f32_16x16x32_bf16 v[132:135], v[144:147], v[160:163], v[132:135]
	v_mfma_f32_16x16x32_bf16 v[132:135], v[148:151], v[164:167], v[132:135]
	v_mfma_f32_16x16x32_bf16 v[116:119], v[144:147], v[168:171], v[116:119]
	v_mfma_f32_16x16x32_bf16 v[116:119], v[148:151], v[172:175], v[116:119]
	v_mfma_f32_16x16x32_bf16 v[100:103], v[144:147], v[176:179], v[100:103]
	v_mfma_f32_16x16x32_bf16 v[100:103], v[148:151], v[180:183], v[100:103]
	v_mfma_f32_16x16x32_bf16 v[76:79], v[144:147], v[212:215], v[76:79]
	v_mfma_f32_16x16x32_bf16 v[76:79], v[148:151], v[216:219], v[76:79]
	v_mfma_f32_16x16x32_bf16 v[128:131], v[152:155], v[160:163], v[128:131]
	v_mfma_f32_16x16x32_bf16 v[128:131], v[156:159], v[164:167], v[128:131]
	v_mfma_f32_16x16x32_bf16 v[112:115], v[152:155], v[168:171], v[112:115]
	v_mfma_f32_16x16x32_bf16 v[112:115], v[156:159], v[172:175], v[112:115]
	v_mfma_f32_16x16x32_bf16 v[96:99], v[152:155], v[176:179], v[96:99]
	v_mfma_f32_16x16x32_bf16 v[96:99], v[156:159], v[180:183], v[96:99]
	v_mfma_f32_16x16x32_bf16 v[72:75], v[152:155], v[212:215], v[72:75]
	v_mfma_f32_16x16x32_bf16 v[72:75], v[156:159], v[216:219], v[72:75]
	s_barrier
	s_add_i32 s54, s33, s18
	s_mov_b32 m0, s54
	ds_read_b128 v[160:163], v233 offset:16384
	ds_read_b128 v[164:167], v233 offset:17408
	ds_read_b128 v[168:171], v233 offset:18432
	ds_read_b128 v[172:175], v233 offset:19456
	ds_read_b128 v[176:179], v233 offset:20480
	ds_read_b128 v[180:183], v233 offset:21504
	ds_read_b128 v[212:215], v233 offset:22528
	ds_read_b128 v[216:219], v233 offset:23552
	global_load_lds_dwordx4 v196, s[96:97]
	s_add_i32 m0, s54, 0x2000
	s_add_u32 s54, s96, 0x4000
	s_addc_u32 s55, s97, 0
	s_add_i32 s56, s42, s18
	global_load_lds_dwordx4 v200, s[96:97]
	s_mov_b32 m0, s56
	s_nop 0
	global_load_lds_dwordx4 v196, s[54:55]
	s_add_i32 m0, s56, 0x2000
	s_nop 0
	global_load_lds_dwordx4 v200, s[54:55]
	v_lshl_add_u64 v[220:221], vcc, 0, v[194:195]
	s_mov_b32 m0, s19
	s_nop 0
	global_load_lds_dwordx4 v[220:221], off
	v_lshl_add_u64 v[220:221], vcc, 0, v[198:199]
	s_mov_b32 m0, s20
	s_nop 0
	global_load_lds_dwordx4 v[220:221], off
	s_waitcnt vmcnt(8)
	s_waitcnt lgkmcnt(0)
	s_barrier
	s_waitcnt lgkmcnt(0)
	v_mfma_f32_16x16x32_bf16 v[60:63], v[64:67], v[160:163], v[60:63]
	v_mfma_f32_16x16x32_bf16 v[60:63], v[68:71], v[164:167], v[60:63]
	v_mfma_f32_16x16x32_bf16 v[44:47], v[64:67], v[168:171], v[44:47]
	v_mfma_f32_16x16x32_bf16 v[44:47], v[68:71], v[172:175], v[44:47]
	v_mfma_f32_16x16x32_bf16 v[28:31], v[64:67], v[176:179], v[28:31]
	v_mfma_f32_16x16x32_bf16 v[28:31], v[68:71], v[180:183], v[28:31]
	v_mfma_f32_16x16x32_bf16 v[12:15], v[64:67], v[212:215], v[12:15]
	v_mfma_f32_16x16x32_bf16 v[12:15], v[68:71], v[216:219], v[12:15]
	v_mfma_f32_16x16x32_bf16 v[56:59], v[80:83], v[160:163], v[56:59]
	v_mfma_f32_16x16x32_bf16 v[56:59], v[84:87], v[164:167], v[56:59]
	v_mfma_f32_16x16x32_bf16 v[40:43], v[80:83], v[168:171], v[40:43]
	v_mfma_f32_16x16x32_bf16 v[40:43], v[84:87], v[172:175], v[40:43]
	v_mfma_f32_16x16x32_bf16 v[24:27], v[80:83], v[176:179], v[24:27]
	v_mfma_f32_16x16x32_bf16 v[24:27], v[84:87], v[180:183], v[24:27]
	v_mfma_f32_16x16x32_bf16 v[8:11], v[80:83], v[212:215], v[8:11]
	v_mfma_f32_16x16x32_bf16 v[8:11], v[84:87], v[216:219], v[8:11]
	v_mfma_f32_16x16x32_bf16 v[52:55], v[144:147], v[160:163], v[52:55]
	v_mfma_f32_16x16x32_bf16 v[52:55], v[148:151], v[164:167], v[52:55]
	v_mfma_f32_16x16x32_bf16 v[36:39], v[144:147], v[168:171], v[36:39]
	v_mfma_f32_16x16x32_bf16 v[36:39], v[148:151], v[172:175], v[36:39]
	v_mfma_f32_16x16x32_bf16 v[20:23], v[144:147], v[176:179], v[20:23]
	v_mfma_f32_16x16x32_bf16 v[20:23], v[148:151], v[180:183], v[20:23]
	v_mfma_f32_16x16x32_bf16 v[4:7], v[144:147], v[212:215], v[4:7]
	v_mfma_f32_16x16x32_bf16 v[4:7], v[148:151], v[216:219], v[4:7]
	v_mfma_f32_16x16x32_bf16 v[48:51], v[152:155], v[160:163], v[48:51]
	v_mfma_f32_16x16x32_bf16 v[48:51], v[156:159], v[164:167], v[48:51]
	v_mfma_f32_16x16x32_bf16 v[32:35], v[152:155], v[168:171], v[32:35]
	v_mfma_f32_16x16x32_bf16 v[32:35], v[156:159], v[172:175], v[32:35]
	v_mfma_f32_16x16x32_bf16 v[16:19], v[152:155], v[176:179], v[16:19]
	v_mfma_f32_16x16x32_bf16 v[16:19], v[156:159], v[180:183], v[16:19]
	v_mfma_f32_16x16x32_bf16 v[0:3], v[152:155], v[212:215], v[0:3]
	v_mfma_f32_16x16x32_bf16 v[0:3], v[156:159], v[216:219], v[0:3]
	s_barrier
; #define PG8_STAGE(bufoff, gbase, voff) do { _Pragma("unroll") for (int _i = 0; _i < 2; ++_i) \
;         __builtin_amdgcn_global_load_lds((const unsigned*)((const char*)(gbase) + (voff)[_i]), (LAS unsigned*)(lds + (bufoff) + ldsw + _i * 8192), 16, 0, 0); } while (0)
; #define PG8_LDA(dst, b, h) do { _Pragma("unroll") for (int m = 0; m < 4; ++m) _Pragma("unroll") for (int k = 0; k < 2; ++k) dst[m][k] = *(const LAS bf16x8*)(lds + PG8_SA(b, h) + aoff + m * 2048 + k * 1024); } while (0)
; #define PG8_LDB(dst, b, h) do { _Pragma("unroll") for (int n = 0; n < 2; ++n) _Pragma("unroll") for (int k = 0; k < 2; ++k) dst[n][k] = *(const LAS bf16x8*)(lds + PG8_SB(b, h) + boff + n * 2048 + k * 1024); } while (0)
; #define PG8_MMA(ai, bj, At, Bt) do { __builtin_amdgcn_s_setprio(1); _Pragma("unroll") for (int m = 0; m < 4; ++m) _Pragma("unroll") for (int n = 0; n < 2; ++n) _Pragma("unroll") for (int k = 0; k < 2; ++k) \
;         acc[ai][bj][m][n] = __builtin_amdgcn_mfma_f32_16x16x32_bf16(Bt[n][k], At[m][k], acc[ai][bj][m][n], 0, 0, 0); __builtin_amdgcn_s_setprio(0); } while (0)
; #define PG8_WAIT_V(n) asm volatile("s_waitcnt vmcnt(" #n ")" ::: "memory")
; #define PG8_WAIT_L(n) asm volatile("s_waitcnt lgkmcnt(" #n ")" ::: "memory")
; #define PG8_BAR __builtin_amdgcn_s_barrier()
; #define PG8_SCHED __builtin_amdgcn_sched_barrier(0)
; template <bool ALIGN_EPI, class Epi, class Sched>
; __device__ __forceinline__ void gemm_phase(LAS unsigned char* lds, const int lda, const int ldb, const int K, const Sched& S, const Epi& E, const size_t kstepA = (size_t)(BK * 2), const size_t kstepB = (size_t)(BK * 2)) {
;     ...
;             PG8_LDB(B0, 1, 0); PG8_LDB(B1, 1, 1); PG8_SCHED; PG8_LDA(At, 1, 0); PG8_STAGE(PG8_SA(0, 1), a2 + hstepA, voffA);
;             PG8_WAIT_V(8); PG8_WAIT_L(0); PG8_BAR; PG8_MMA(0, 0, At, B0); PG8_MMA(0, 1, At, B1); PG8_BAR; PG8_SCHED;
;             PG8_LDA(At, 1, 1); PG8_STAGE(PG8_SB(1, 0), b3, voffB); PG8_STAGE(PG8_SB(1, 1), b3 + hstepB, voffB); PG8_STAGE(PG8_SA(1, 0), a3, voffA);
;             PG8_WAIT_V(8); PG8_WAIT_L(0); PG8_BAR; PG8_MMA(1, 0, At, B0); PG8_MMA(1, 1, At, B1); PG8_BAR; PG8_SCHED;
;         }
	s_add_i32 s56, 0, 0x18000
	s_add_i32 s57, 0, 0x1c000
	v_add_u32_e32 v84, s56, v191
	v_add_u32_e32 v156, s57, v191
	ds_read_b128 v[64:67], v84
	ds_read_b128 v[68:71], v84 offset:1024
	ds_read_b128 v[80:83], v84 offset:2048
	ds_read_b128 v[84:87], v84 offset:3072
	ds_read_b128 v[144:147], v156
	ds_read_b128 v[148:151], v156 offset:1024
	ds_read_b128 v[152:155], v156 offset:2048
	ds_read_b128 v[156:159], v156 offset:3072
	s_add_u32 s54, vcc_lo, 0x4000
	s_addc_u32 s55, vcc_hi, 0
	s_mov_b32 m0, s21
	ds_read_b128 v[160:163], v233 offset:32768
	ds_read_b128 v[164:167], v233 offset:33792
	ds_read_b128 v[168:171], v233 offset:34816
	ds_read_b128 v[172:175], v233 offset:35840
	ds_read_b128 v[176:179], v233 offset:36864
	ds_read_b128 v[180:183], v233 offset:37888
	ds_read_b128 v[212:215], v233 offset:38912
	ds_read_b128 v[216:219], v233 offset:39936
	global_load_lds_dwordx4 v194, s[54:55]
	s_mov_b32 m0, s22
	s_nop 0
	global_load_lds_dwordx4 v198, s[54:55]
	s_waitcnt vmcnt(8)
	s_waitcnt lgkmcnt(0)
	s_barrier
	s_waitcnt lgkmcnt(0)
	v_mfma_f32_16x16x32_bf16 v[140:143], v[64:67], v[160:163], v[140:143]
	v_mfma_f32_16x16x32_bf16 v[140:143], v[68:71], v[164:167], v[140:143]
	v_mfma_f32_16x16x32_bf16 v[124:127], v[64:67], v[168:171], v[124:127]
	v_mfma_f32_16x16x32_bf16 v[124:127], v[68:71], v[172:175], v[124:127]
	v_mfma_f32_16x16x32_bf16 v[108:111], v[64:67], v[176:179], v[108:111]
	v_mfma_f32_16x16x32_bf16 v[108:111], v[68:71], v[180:183], v[108:111]
	v_mfma_f32_16x16x32_bf16 v[92:95], v[64:67], v[212:215], v[92:95]
	v_mfma_f32_16x16x32_bf16 v[92:95], v[68:71], v[216:219], v[92:95]
	v_mfma_f32_16x16x32_bf16 v[136:139], v[80:83], v[160:163], v[136:139]
	v_mfma_f32_16x16x32_bf16 v[136:139], v[84:87], v[164:167], v[136:139]
	v_mfma_f32_16x16x32_bf16 v[120:123], v[80:83], v[168:171], v[120:123]
	v_mfma_f32_16x16x32_bf16 v[120:123], v[84:87], v[172:175], v[120:123]
	v_mfma_f32_16x16x32_bf16 v[104:107], v[80:83], v[176:179], v[104:107]
	v_mfma_f32_16x16x32_bf16 v[104:107], v[84:87], v[180:183], v[104:107]
	v_mfma_f32_16x16x32_bf16 v[88:91], v[80:83], v[212:215], v[88:91]
	v_mfma_f32_16x16x32_bf16 v[88:91], v[84:87], v[216:219], v[88:91]
	v_mfma_f32_16x16x32_bf16 v[132:135], v[144:147], v[160:163], v[132:135]
	v_mfma_f32_16x16x32_bf16 v[132:135], v[148:151], v[164:167], v[132:135]
	v_mfma_f32_16x16x32_bf16 v[116:119], v[144:147], v[168:171], v[116:119]
	v_mfma_f32_16x16x32_bf16 v[116:119], v[148:151], v[172:175], v[116:119]
	v_mfma_f32_16x16x32_bf16 v[100:103], v[144:147], v[176:179], v[100:103]
	v_mfma_f32_16x16x32_bf16 v[100:103], v[148:151], v[180:183], v[100:103]
	v_mfma_f32_16x16x32_bf16 v[76:79], v[144:147], v[212:215], v[76:79]
	v_mfma_f32_16x16x32_bf16 v[76:79], v[148:151], v[216:219], v[76:79]
	v_mfma_f32_16x16x32_bf16 v[128:131], v[152:155], v[160:163], v[128:131]
	v_mfma_f32_16x16x32_bf16 v[128:131], v[156:159], v[164:167], v[128:131]
	v_mfma_f32_16x16x32_bf16 v[112:115], v[152:155], v[168:171], v[112:115]
	v_mfma_f32_16x16x32_bf16 v[112:115], v[156:159], v[172:175], v[112:115]
	v_mfma_f32_16x16x32_bf16 v[96:99], v[152:155], v[176:179], v[96:99]
	v_mfma_f32_16x16x32_bf16 v[96:99], v[156:159], v[180:183], v[96:99]
	v_mfma_f32_16x16x32_bf16 v[72:75], v[152:155], v[212:215], v[72:75]
	v_mfma_f32_16x16x32_bf16 v[72:75], v[156:159], v[216:219], v[72:75]
	s_barrier
	s_add_u32 s54, s96, 0x40000
	s_addc_u32 s55, s97, 0
	s_add_i32 s56, s56, s18
	s_mov_b32 m0, s56
	ds_read_b128 v[160:163], v233 offset:49152
	ds_read_b128 v[164:167], v233 offset:50176
	ds_read_b128 v[168:171], v233 offset:51200
	ds_read_b128 v[172:175], v233 offset:52224
	ds_read_b128 v[176:179], v233 offset:53248
	ds_read_b128 v[180:183], v233 offset:54272
	ds_read_b128 v[212:215], v233 offset:55296
	ds_read_b128 v[216:219], v233 offset:56320
	global_load_lds_dwordx4 v196, s[54:55]
	s_add_i32 m0, s56, 0x2000
	s_nop 0
	global_load_lds_dwordx4 v200, s[54:55]
	s_add_u32 s54, s96, 0x44000
	s_addc_u32 s55, s97, 0
	s_add_i32 s56, s57, s18
	s_mov_b32 m0, s56
	s_nop 0
	global_load_lds_dwordx4 v196, s[54:55]
	s_add_i32 m0, s56, 0x2000
	s_nop 0
	global_load_lds_dwordx4 v200, s[54:55]
	s_mov_b32 m0, s30
	s_nop 0
	global_load_lds_dwordx4 v194, s[94:95]
	s_mov_b32 m0, s31
	s_nop 0
	global_load_lds_dwordx4 v198, s[94:95]
	s_waitcnt vmcnt(8)
	s_waitcnt lgkmcnt(0)
	s_barrier
	s_waitcnt lgkmcnt(0)
	v_mfma_f32_16x16x32_bf16 v[60:63], v[64:67], v[160:163], v[60:63]
	v_mfma_f32_16x16x32_bf16 v[60:63], v[68:71], v[164:167], v[60:63]
	v_mfma_f32_16x16x32_bf16 v[44:47], v[64:67], v[168:171], v[44:47]
	v_mfma_f32_16x16x32_bf16 v[44:47], v[68:71], v[172:175], v[44:47]
	v_mfma_f32_16x16x32_bf16 v[28:31], v[64:67], v[176:179], v[28:31]
	v_mfma_f32_16x16x32_bf16 v[28:31], v[68:71], v[180:183], v[28:31]
	v_mfma_f32_16x16x32_bf16 v[12:15], v[64:67], v[212:215], v[12:15]
	v_mfma_f32_16x16x32_bf16 v[12:15], v[68:71], v[216:219], v[12:15]
	v_mfma_f32_16x16x32_bf16 v[56:59], v[80:83], v[160:163], v[56:59]
	v_mfma_f32_16x16x32_bf16 v[56:59], v[84:87], v[164:167], v[56:59]
	v_mfma_f32_16x16x32_bf16 v[40:43], v[80:83], v[168:171], v[40:43]
	v_mfma_f32_16x16x32_bf16 v[40:43], v[84:87], v[172:175], v[40:43]
	v_mfma_f32_16x16x32_bf16 v[24:27], v[80:83], v[176:179], v[24:27]
	v_mfma_f32_16x16x32_bf16 v[24:27], v[84:87], v[180:183], v[24:27]
	v_mfma_f32_16x16x32_bf16 v[8:11], v[80:83], v[212:215], v[8:11]
	v_mfma_f32_16x16x32_bf16 v[8:11], v[84:87], v[216:219], v[8:11]
	v_mfma_f32_16x16x32_bf16 v[52:55], v[144:147], v[160:163], v[52:55]
	v_mfma_f32_16x16x32_bf16 v[52:55], v[148:151], v[164:167], v[52:55]
	v_mfma_f32_16x16x32_bf16 v[36:39], v[144:147], v[168:171], v[36:39]
	v_mfma_f32_16x16x32_bf16 v[36:39], v[148:151], v[172:175], v[36:39]
	v_mfma_f32_16x16x32_bf16 v[20:23], v[144:147], v[176:179], v[20:23]
	v_mfma_f32_16x16x32_bf16 v[20:23], v[148:151], v[180:183], v[20:23]
	v_mfma_f32_16x16x32_bf16 v[4:7], v[144:147], v[212:215], v[4:7]
	v_mfma_f32_16x16x32_bf16 v[4:7], v[148:151], v[216:219], v[4:7]
	v_mfma_f32_16x16x32_bf16 v[48:51], v[152:155], v[160:163], v[48:51]
	v_mfma_f32_16x16x32_bf16 v[48:51], v[156:159], v[164:167], v[48:51]
	v_mfma_f32_16x16x32_bf16 v[32:35], v[152:155], v[168:171], v[32:35]
	v_mfma_f32_16x16x32_bf16 v[32:35], v[156:159], v[172:175], v[32:35]
	v_mfma_f32_16x16x32_bf16 v[16:19], v[152:155], v[176:179], v[16:19]
	v_mfma_f32_16x16x32_bf16 v[16:19], v[156:159], v[180:183], v[16:19]
	v_mfma_f32_16x16x32_bf16 v[0:3], v[152:155], v[212:215], v[0:3]
	v_mfma_f32_16x16x32_bf16 v[0:3], v[156:159], v[216:219], v[0:3]
	s_barrier
	s_add_i32 s51, s51, 2
	s_add_u32 s13, s13, 0x80000
	s_addc_u32 s50, s50, 0
	s_add_u32 s82, s82, 0x400000
	s_addc_u32 s83, s83, 0
	s_cmpk_gt_u32 s51, 0x55
	s_cbranch_scc0 .LBB0_218
	s_and_b64 vcc, exec, s[84:85]
	s_cbranch_vccz .LBB0_221
	s_barrier

; #define PG8_STAGE(bufoff, gbase, voff) do { _Pragma("unroll") for (int _i = 0; _i < 2; ++_i) \
;         __builtin_amdgcn_global_load_lds((const unsigned*)((const char*)(gbase) + (voff)[_i]), (LAS unsigned*)(lds + (bufoff) + ldsw + _i * 8192), 16, 0, 0); } while (0)
; #define PG8_LDA(dst, b, h) do { _Pragma("unroll") for (int m = 0; m < 4; ++m) _Pragma("unroll") for (int k = 0; k < 2; ++k) dst[m][k] = *(const LAS bf16x8*)(lds + PG8_SA(b, h) + aoff + m * 2048 + k * 1024); } while (0)
; #define PG8_LDB(dst, b, h) do { _Pragma("unroll") for (int n = 0; n < 2; ++n) _Pragma("unroll") for (int k = 0; k < 2; ++k) dst[n][k] = *(const LAS bf16x8*)(lds + PG8_SB(b, h) + boff + n * 2048 + k * 1024); } while (0)
; #define PG8_MMA(ai, bj, At, Bt) do { __builtin_amdgcn_s_setprio(1); _Pragma("unroll") for (int m = 0; m < 4; ++m) _Pragma("unroll") for (int n = 0; n < 2; ++n) _Pragma("unroll") for (int k = 0; k < 2; ++k) \
;         acc[ai][bj][m][n] = __builtin_amdgcn_mfma_f32_16x16x32_bf16(Bt[n][k], At[m][k], acc[ai][bj][m][n], 0, 0, 0); __builtin_amdgcn_s_setprio(0); } while (0)
; #define PG8_WAIT_V(n) asm volatile("s_waitcnt vmcnt(" #n ")" ::: "memory")
; #define PG8_WAIT_L(n) asm volatile("s_waitcnt lgkmcnt(" #n ")" ::: "memory")
; template <bool ALIGN_EPI, class Epi, class Sched>
; __device__ __forceinline__ void gemm_phase(LAS unsigned char* lds, const int lda, const int ldb, const int K, const Sched& S, const Epi& E, const size_t kstepA = (size_t)(BK * 2), const size_t kstepB = (size_t)(BK * 2)) {
;     ...
;         for (int t = 0; t < nt; t += 2) {
;             const bool last = (t == nt - 2);
;             const char* a1 = cA + (size_t)(t + 1) * kstepA;
;             const char* a2 = last ? nA : cA + (size_t)(t + 2) * kstepA; const char* b2 = last ? nB : cB + (size_t)(t + 2) * kstep;
;             const char* a3 = a2 + kstepA; const char* b3 = b2 + kstep;
;             PG8_LDB(B0, 0, 0); PG8_LDB(B1, 0, 1); PG8_SCHED; PG8_LDA(At, 0, 0); PG8_STAGE(PG8_SA(1, 1), a1 + hstepA, voffA);
;             PG8_WAIT_V(8); PG8_WAIT_L(0); PG8_BAR; PG8_MMA(0, 0, At, B0); PG8_MMA(0, 1, At, B1); PG8_BAR; PG8_SCHED;
;             PG8_LDA(At, 0, 1); PG8_STAGE(PG8_SB(0, 0), b2, voffB); PG8_STAGE(PG8_SB(0, 1), b2 + hstepB, voffB); PG8_STAGE(PG8_SA(0, 0), a2, voffA);
;             PG8_WAIT_V(8); PG8_WAIT_L(0); PG8_BAR; PG8_MMA(1, 0, At, B0); PG8_MMA(1, 1, At, B1); PG8_BAR; PG8_SCHED;
.LBB0_347:
	ds_read_b128 v[158:161], v195
	ds_read_b128 v[162:165], v195 offset:1024
	ds_read_b128 v[166:169], v195 offset:2048
	ds_read_b128 v[198:201], v195 offset:3072
	ds_read_b128 v[202:205], v196
	ds_read_b128 v[206:209], v196 offset:1024
	ds_read_b128 v[210:213], v196 offset:2048
	ds_read_b128 v[214:217], v196 offset:3072
	s_add_u32 s59, s16, 0x1fc000
	s_addc_u32 s60, s17, 0
	s_cmp_eq_u32 s58, 28
	s_cselect_b32 s94, s6, s59
	s_cselect_b32 s95, s7, s60
	s_cselect_b32 s92, s14, s55
	s_cselect_b32 s93, s15, s57
	s_add_u32 s82, s94, 0x200000
	s_addc_u32 s83, s95, 0
	s_add_i32 m0, s20, 0xc000
	ds_read_b128 v[218:221], v193
	ds_read_b128 v[222:225], v193 offset:1024
	ds_read_b128 v[226:229], v193 offset:2048
	ds_read_b128 v[230:233], v193 offset:3072
	ds_read_b128 v[234:237], v193 offset:4096
	ds_read_b128 v[238:241], v193 offset:5120
	ds_read_b128 v[242:245], v193 offset:6144
	ds_read_b128 v[246:249], v193 offset:7168
	global_load_lds_dwordx4 v150, s[16:17]
	s_add_i32 m0, s20, 0xe000
	s_nop 0
	global_load_lds_dwordx4 v152, s[16:17]
	s_waitcnt vmcnt(8)
	s_waitcnt lgkmcnt(0)
	s_barrier
	s_waitcnt lgkmcnt(0)
	v_mfma_f32_16x16x32_bf16 v[124:127], v[158:161], v[218:221], v[124:127]
	v_mfma_f32_16x16x32_bf16 v[124:127], v[162:165], v[222:225], v[124:127]
	v_mfma_f32_16x16x32_bf16 v[108:111], v[158:161], v[226:229], v[108:111]
	v_mfma_f32_16x16x32_bf16 v[108:111], v[162:165], v[230:233], v[108:111]
	v_mfma_f32_16x16x32_bf16 v[92:95], v[158:161], v[234:237], v[92:95]
	v_mfma_f32_16x16x32_bf16 v[92:95], v[162:165], v[238:241], v[92:95]
	v_mfma_f32_16x16x32_bf16 v[76:79], v[158:161], v[242:245], v[76:79]
	v_mfma_f32_16x16x32_bf16 v[76:79], v[162:165], v[246:249], v[76:79]
	v_mfma_f32_16x16x32_bf16 v[120:123], v[166:169], v[218:221], v[120:123]
	v_mfma_f32_16x16x32_bf16 v[120:123], v[198:201], v[222:225], v[120:123]
	v_mfma_f32_16x16x32_bf16 v[104:107], v[166:169], v[226:229], v[104:107]
	v_mfma_f32_16x16x32_bf16 v[104:107], v[198:201], v[230:233], v[104:107]
	v_mfma_f32_16x16x32_bf16 v[88:91], v[166:169], v[234:237], v[88:91]
	v_mfma_f32_16x16x32_bf16 v[88:91], v[198:201], v[238:241], v[88:91]
	v_mfma_f32_16x16x32_bf16 v[72:75], v[166:169], v[242:245], v[72:75]
	v_mfma_f32_16x16x32_bf16 v[72:75], v[198:201], v[246:249], v[72:75]
	v_mfma_f32_16x16x32_bf16 v[116:119], v[202:205], v[218:221], v[116:119]
	v_mfma_f32_16x16x32_bf16 v[116:119], v[206:209], v[222:225], v[116:119]
	v_mfma_f32_16x16x32_bf16 v[100:103], v[202:205], v[226:229], v[100:103]
	v_mfma_f32_16x16x32_bf16 v[100:103], v[206:209], v[230:233], v[100:103]
	v_mfma_f32_16x16x32_bf16 v[84:87], v[202:205], v[234:237], v[84:87]
	v_mfma_f32_16x16x32_bf16 v[84:87], v[206:209], v[238:241], v[84:87]
	v_mfma_f32_16x16x32_bf16 v[68:71], v[202:205], v[242:245], v[68:71]
	v_mfma_f32_16x16x32_bf16 v[68:71], v[206:209], v[246:249], v[68:71]
	v_mfma_f32_16x16x32_bf16 v[112:115], v[210:213], v[218:221], v[112:115]
	v_mfma_f32_16x16x32_bf16 v[112:115], v[214:217], v[222:225], v[112:115]
	v_mfma_f32_16x16x32_bf16 v[96:99], v[210:213], v[226:229], v[96:99]
	v_mfma_f32_16x16x32_bf16 v[96:99], v[214:217], v[230:233], v[96:99]
	v_mfma_f32_16x16x32_bf16 v[80:83], v[210:213], v[234:237], v[80:83]
	v_mfma_f32_16x16x32_bf16 v[80:83], v[214:217], v[238:241], v[80:83]
	v_mfma_f32_16x16x32_bf16 v[64:67], v[210:213], v[242:245], v[64:67]
	v_mfma_f32_16x16x32_bf16 v[64:67], v[214:217], v[246:249], v[64:67]
	s_barrier
	s_add_i32 s59, s42, s19
	s_mov_b32 m0, s59
	ds_read_b128 v[218:221], v193 offset:16384
	ds_read_b128 v[222:225], v193 offset:17408
	ds_read_b128 v[226:229], v193 offset:18432
	ds_read_b128 v[230:233], v193 offset:19456
	ds_read_b128 v[234:237], v193 offset:20480
	ds_read_b128 v[238:241], v193 offset:21504
	ds_read_b128 v[242:245], v193 offset:22528
	ds_read_b128 v[246:249], v193 offset:23552
	global_load_lds_dwordx4 v130, s[92:93]
	s_add_i32 m0, s59, 0x2000
	s_add_u32 s60, s92, 0x4000
	s_addc_u32 s61, s93, 0
	s_add_i32 s59, s43, s19
	global_load_lds_dwordx4 v134, s[92:93]
	s_mov_b32 m0, s59
	s_nop 0
	global_load_lds_dwordx4 v130, s[60:61]
	s_add_i32 m0, s59, 0x2000
	s_nop 0
	global_load_lds_dwordx4 v134, s[60:61]
	s_mov_b32 m0, s20
	s_nop 0
	global_load_lds_dwordx4 v128, s[94:95]
	s_mov_b32 m0, s21
	s_nop 0
	global_load_lds_dwordx4 v132, s[94:95]
	s_waitcnt vmcnt(8)
	s_waitcnt lgkmcnt(0)
	s_barrier
	s_waitcnt lgkmcnt(0)
	v_mfma_f32_16x16x32_bf16 v[60:63], v[158:161], v[218:221], v[60:63]
	v_mfma_f32_16x16x32_bf16 v[60:63], v[162:165], v[222:225], v[60:63]
	v_mfma_f32_16x16x32_bf16 v[44:47], v[158:161], v[226:229], v[44:47]
	v_mfma_f32_16x16x32_bf16 v[44:47], v[162:165], v[230:233], v[44:47]
	v_mfma_f32_16x16x32_bf16 v[28:31], v[158:161], v[234:237], v[28:31]
	v_mfma_f32_16x16x32_bf16 v[28:31], v[162:165], v[238:241], v[28:31]
	v_mfma_f32_16x16x32_bf16 v[12:15], v[158:161], v[242:245], v[12:15]
	v_mfma_f32_16x16x32_bf16 v[12:15], v[162:165], v[246:249], v[12:15]
	v_mfma_f32_16x16x32_bf16 v[56:59], v[166:169], v[218:221], v[56:59]
	v_mfma_f32_16x16x32_bf16 v[56:59], v[198:201], v[222:225], v[56:59]
	v_mfma_f32_16x16x32_bf16 v[40:43], v[166:169], v[226:229], v[40:43]
	v_mfma_f32_16x16x32_bf16 v[40:43], v[198:201], v[230:233], v[40:43]
	v_mfma_f32_16x16x32_bf16 v[24:27], v[166:169], v[234:237], v[24:27]
	v_mfma_f32_16x16x32_bf16 v[24:27], v[198:201], v[238:241], v[24:27]
	v_mfma_f32_16x16x32_bf16 v[8:11], v[166:169], v[242:245], v[8:11]
	v_mfma_f32_16x16x32_bf16 v[8:11], v[198:201], v[246:249], v[8:11]
	v_mfma_f32_16x16x32_bf16 v[52:55], v[202:205], v[218:221], v[52:55]
	v_mfma_f32_16x16x32_bf16 v[52:55], v[206:209], v[222:225], v[52:55]
	v_mfma_f32_16x16x32_bf16 v[36:39], v[202:205], v[226:229], v[36:39]
	v_mfma_f32_16x16x32_bf16 v[36:39], v[206:209], v[230:233], v[36:39]
	v_mfma_f32_16x16x32_bf16 v[20:23], v[202:205], v[234:237], v[20:23]
	v_mfma_f32_16x16x32_bf16 v[20:23], v[206:209], v[238:241], v[20:23]
	v_mfma_f32_16x16x32_bf16 v[4:7], v[202:205], v[242:245], v[4:7]
	v_mfma_f32_16x16x32_bf16 v[4:7], v[206:209], v[246:249], v[4:7]
	v_mfma_f32_16x16x32_bf16 v[48:51], v[210:213], v[218:221], v[48:51]
	v_mfma_f32_16x16x32_bf16 v[48:51], v[214:217], v[222:225], v[48:51]
	v_mfma_f32_16x16x32_bf16 v[32:35], v[210:213], v[226:229], v[32:35]
	v_mfma_f32_16x16x32_bf16 v[32:35], v[214:217], v[230:233], v[32:35]
	v_mfma_f32_16x16x32_bf16 v[16:19], v[210:213], v[234:237], v[16:19]
	v_mfma_f32_16x16x32_bf16 v[16:19], v[214:217], v[238:241], v[16:19]
	v_mfma_f32_16x16x32_bf16 v[0:3], v[210:213], v[242:245], v[0:3]
	v_mfma_f32_16x16x32_bf16 v[0:3], v[214:217], v[246:249], v[0:3]
	s_barrier
; #define PG8_STAGE(bufoff, gbase, voff) do { _Pragma("unroll") for (int _i = 0; _i < 2; ++_i) \
;         __builtin_amdgcn_global_load_lds((const unsigned*)((const char*)(gbase) + (voff)[_i]), (LAS unsigned*)(lds + (bufoff) + ldsw + _i * 8192), 16, 0, 0); } while (0)
; #define PG8_LDA(dst, b, h) do { _Pragma("unroll") for (int m = 0; m < 4; ++m) _Pragma("unroll") for (int k = 0; k < 2; ++k) dst[m][k] = *(const LAS bf16x8*)(lds + PG8_SA(b, h) + aoff + m * 2048 + k * 1024); } while (0)
; #define PG8_LDB(dst, b, h) do { _Pragma("unroll") for (int n = 0; n < 2; ++n) _Pragma("unroll") for (int k = 0; k < 2; ++k) dst[n][k] = *(const LAS bf16x8*)(lds + PG8_SB(b, h) + boff + n * 2048 + k * 1024); } while (0)
; #define PG8_MMA(ai, bj, At, Bt) do { __builtin_amdgcn_s_setprio(1); _Pragma("unroll") for (int m = 0; m < 4; ++m) _Pragma("unroll") for (int n = 0; n < 2; ++n) _Pragma("unroll") for (int k = 0; k < 2; ++k) \
;         acc[ai][bj][m][n] = __builtin_amdgcn_mfma_f32_16x16x32_bf16(Bt[n][k], At[m][k], acc[ai][bj][m][n], 0, 0, 0); __builtin_amdgcn_s_setprio(0); } while (0)
; #define PG8_WAIT_V(n) asm volatile("s_waitcnt vmcnt(" #n ")" ::: "memory")
; #define PG8_WAIT_L(n) asm volatile("s_waitcnt lgkmcnt(" #n ")" ::: "memory")
; #define PG8_BAR __builtin_amdgcn_s_barrier()
; #define PG8_SCHED __builtin_amdgcn_sched_barrier(0)
; template <bool ALIGN_EPI, class Epi, class Sched>
; __device__ __forceinline__ void gemm_phase(LAS unsigned char* lds, const int lda, const int ldb, const int K, const Sched& S, const Epi& E, const size_t kstepA = (size_t)(BK * 2), const size_t kstepB = (size_t)(BK * 2)) {
;     ...
;             PG8_LDB(B0, 1, 0); PG8_LDB(B1, 1, 1); PG8_SCHED; PG8_LDA(At, 1, 0); PG8_STAGE(PG8_SA(0, 1), a2 + hstepA, voffA);
;             PG8_WAIT_V(8); PG8_WAIT_L(0); PG8_BAR; PG8_MMA(0, 0, At, B0); PG8_MMA(0, 1, At, B1); PG8_BAR; PG8_SCHED;
;             PG8_LDA(At, 1, 1); PG8_STAGE(PG8_SB(1, 0), b3, voffB); PG8_STAGE(PG8_SB(1, 1), b3 + hstepB, voffB); PG8_STAGE(PG8_SA(1, 0), a3, voffA);
;             PG8_WAIT_V(8); PG8_WAIT_L(0); PG8_BAR; PG8_MMA(1, 0, At, B0); PG8_MMA(1, 1, At, B1); PG8_BAR; PG8_SCHED;
;         }
	s_add_i32 s59, 0, 0x18000
	v_add_u32_e32 v136, s59, v141
	s_add_i32 s64, 0, 0x1c000
	ds_read_b128 v[158:161], v136
	ds_read_b128 v[162:165], v136 offset:1024
	ds_read_b128 v[166:169], v136 offset:2048
	ds_read_b128 v[198:201], v136 offset:3072
	v_add_u32_e32 v136, s64, v141
	ds_read_b128 v[202:205], v136
	ds_read_b128 v[206:209], v136 offset:1024
	ds_read_b128 v[210:213], v136 offset:2048
	ds_read_b128 v[214:217], v136 offset:3072
	s_add_u32 s60, s94, 0x4000
	s_addc_u32 s61, s95, 0
	s_mov_b32 m0, s22
	ds_read_b128 v[218:221], v193 offset:32768
	ds_read_b128 v[222:225], v193 offset:33792
	ds_read_b128 v[226:229], v193 offset:34816
	ds_read_b128 v[230:233], v193 offset:35840
	ds_read_b128 v[234:237], v193 offset:36864
	ds_read_b128 v[238:241], v193 offset:37888
	ds_read_b128 v[242:245], v193 offset:38912
	ds_read_b128 v[246:249], v193 offset:39936
	global_load_lds_dwordx4 v128, s[60:61]
	s_mov_b32 m0, s23
	s_nop 0
	global_load_lds_dwordx4 v132, s[60:61]
	s_waitcnt vmcnt(8)
	s_waitcnt lgkmcnt(0)
	s_barrier
	s_waitcnt lgkmcnt(0)
	v_mfma_f32_16x16x32_bf16 v[124:127], v[158:161], v[218:221], v[124:127]
	v_mfma_f32_16x16x32_bf16 v[124:127], v[162:165], v[222:225], v[124:127]
	v_mfma_f32_16x16x32_bf16 v[108:111], v[158:161], v[226:229], v[108:111]
	v_mfma_f32_16x16x32_bf16 v[108:111], v[162:165], v[230:233], v[108:111]
	v_mfma_f32_16x16x32_bf16 v[92:95], v[158:161], v[234:237], v[92:95]
	v_mfma_f32_16x16x32_bf16 v[92:95], v[162:165], v[238:241], v[92:95]
	v_mfma_f32_16x16x32_bf16 v[76:79], v[158:161], v[242:245], v[76:79]
	v_mfma_f32_16x16x32_bf16 v[76:79], v[162:165], v[246:249], v[76:79]
	v_mfma_f32_16x16x32_bf16 v[120:123], v[166:169], v[218:221], v[120:123]
	v_mfma_f32_16x16x32_bf16 v[120:123], v[198:201], v[222:225], v[120:123]
	v_mfma_f32_16x16x32_bf16 v[104:107], v[166:169], v[226:229], v[104:107]
	v_mfma_f32_16x16x32_bf16 v[104:107], v[198:201], v[230:233], v[104:107]
	v_mfma_f32_16x16x32_bf16 v[88:91], v[166:169], v[234:237], v[88:91]
	v_mfma_f32_16x16x32_bf16 v[88:91], v[198:201], v[238:241], v[88:91]
	v_mfma_f32_16x16x32_bf16 v[72:75], v[166:169], v[242:245], v[72:75]
	v_mfma_f32_16x16x32_bf16 v[72:75], v[198:201], v[246:249], v[72:75]
	v_mfma_f32_16x16x32_bf16 v[116:119], v[202:205], v[218:221], v[116:119]
	v_mfma_f32_16x16x32_bf16 v[116:119], v[206:209], v[222:225], v[116:119]
	v_mfma_f32_16x16x32_bf16 v[100:103], v[202:205], v[226:229], v[100:103]
	v_mfma_f32_16x16x32_bf16 v[100:103], v[206:209], v[230:233], v[100:103]
	v_mfma_f32_16x16x32_bf16 v[84:87], v[202:205], v[234:237], v[84:87]
	v_mfma_f32_16x16x32_bf16 v[84:87], v[206:209], v[238:241], v[84:87]
	v_mfma_f32_16x16x32_bf16 v[68:71], v[202:205], v[242:245], v[68:71]
	v_mfma_f32_16x16x32_bf16 v[68:71], v[206:209], v[246:249], v[68:71]
	v_mfma_f32_16x16x32_bf16 v[112:115], v[210:213], v[218:221], v[112:115]
	v_mfma_f32_16x16x32_bf16 v[112:115], v[214:217], v[222:225], v[112:115]
	v_mfma_f32_16x16x32_bf16 v[96:99], v[210:213], v[226:229], v[96:99]
	v_mfma_f32_16x16x32_bf16 v[96:99], v[214:217], v[230:233], v[96:99]
	v_mfma_f32_16x16x32_bf16 v[80:83], v[210:213], v[234:237], v[80:83]
	v_mfma_f32_16x16x32_bf16 v[80:83], v[214:217], v[238:241], v[80:83]
	v_mfma_f32_16x16x32_bf16 v[64:67], v[210:213], v[242:245], v[64:67]
	v_mfma_f32_16x16x32_bf16 v[64:67], v[214:217], v[246:249], v[64:67]
	s_barrier
	s_add_u32 s60, s92, 0x80000
	s_addc_u32 s61, s93, 0
	s_add_i32 s59, s59, s19
	s_mov_b32 m0, s59
	ds_read_b128 v[218:221], v193 offset:49152
	ds_read_b128 v[222:225], v193 offset:50176
	ds_read_b128 v[226:229], v193 offset:51200
	ds_read_b128 v[230:233], v193 offset:52224
	ds_read_b128 v[234:237], v193 offset:53248
	ds_read_b128 v[238:241], v193 offset:54272
	ds_read_b128 v[242:245], v193 offset:55296
	ds_read_b128 v[246:249], v193 offset:56320
	global_load_lds_dwordx4 v130, s[60:61]
	s_add_i32 m0, s59, 0x2000
	s_nop 0
	global_load_lds_dwordx4 v134, s[60:61]
	s_add_u32 s60, s92, 0x84000
	s_addc_u32 s61, s93, 0
	s_add_i32 s59, s64, s19
	s_mov_b32 m0, s59
	s_nop 0
	global_load_lds_dwordx4 v130, s[60:61]
	s_add_i32 m0, s59, 0x2000
	s_nop 0
	global_load_lds_dwordx4 v134, s[60:61]
	s_mov_b32 m0, s30
	s_nop 0
	global_load_lds_dwordx4 v128, s[82:83]
	s_mov_b32 m0, s31
	s_nop 0
	global_load_lds_dwordx4 v132, s[82:83]
	s_waitcnt vmcnt(8)
	s_waitcnt lgkmcnt(0)
	s_barrier
	s_waitcnt lgkmcnt(0)
	v_mfma_f32_16x16x32_bf16 v[60:63], v[158:161], v[218:221], v[60:63]
	v_mfma_f32_16x16x32_bf16 v[60:63], v[162:165], v[222:225], v[60:63]
	v_mfma_f32_16x16x32_bf16 v[44:47], v[158:161], v[226:229], v[44:47]
	v_mfma_f32_16x16x32_bf16 v[44:47], v[162:165], v[230:233], v[44:47]
	v_mfma_f32_16x16x32_bf16 v[28:31], v[158:161], v[234:237], v[28:31]
	v_mfma_f32_16x16x32_bf16 v[28:31], v[162:165], v[238:241], v[28:31]
	v_mfma_f32_16x16x32_bf16 v[12:15], v[158:161], v[242:245], v[12:15]
	v_mfma_f32_16x16x32_bf16 v[12:15], v[162:165], v[246:249], v[12:15]
	v_mfma_f32_16x16x32_bf16 v[56:59], v[166:169], v[218:221], v[56:59]
	v_mfma_f32_16x16x32_bf16 v[56:59], v[198:201], v[222:225], v[56:59]
	v_mfma_f32_16x16x32_bf16 v[40:43], v[166:169], v[226:229], v[40:43]
	v_mfma_f32_16x16x32_bf16 v[40:43], v[198:201], v[230:233], v[40:43]
	v_mfma_f32_16x16x32_bf16 v[24:27], v[166:169], v[234:237], v[24:27]
	v_mfma_f32_16x16x32_bf16 v[24:27], v[198:201], v[238:241], v[24:27]
	v_mfma_f32_16x16x32_bf16 v[8:11], v[166:169], v[242:245], v[8:11]
	v_mfma_f32_16x16x32_bf16 v[8:11], v[198:201], v[246:249], v[8:11]
	v_mfma_f32_16x16x32_bf16 v[52:55], v[202:205], v[218:221], v[52:55]
	v_mfma_f32_16x16x32_bf16 v[52:55], v[206:209], v[222:225], v[52:55]
	v_mfma_f32_16x16x32_bf16 v[36:39], v[202:205], v[226:229], v[36:39]
	v_mfma_f32_16x16x32_bf16 v[36:39], v[206:209], v[230:233], v[36:39]
	v_mfma_f32_16x16x32_bf16 v[20:23], v[202:205], v[234:237], v[20:23]
	v_mfma_f32_16x16x32_bf16 v[20:23], v[206:209], v[238:241], v[20:23]
	v_mfma_f32_16x16x32_bf16 v[4:7], v[202:205], v[242:245], v[4:7]
	v_mfma_f32_16x16x32_bf16 v[4:7], v[206:209], v[246:249], v[4:7]
	v_mfma_f32_16x16x32_bf16 v[48:51], v[210:213], v[218:221], v[48:51]
	v_mfma_f32_16x16x32_bf16 v[48:51], v[214:217], v[222:225], v[48:51]
	v_mfma_f32_16x16x32_bf16 v[32:35], v[210:213], v[226:229], v[32:35]
	v_mfma_f32_16x16x32_bf16 v[32:35], v[214:217], v[230:233], v[32:35]
	v_mfma_f32_16x16x32_bf16 v[16:19], v[210:213], v[234:237], v[16:19]
	v_mfma_f32_16x16x32_bf16 v[16:19], v[214:217], v[238:241], v[16:19]
	v_mfma_f32_16x16x32_bf16 v[0:3], v[210:213], v[242:245], v[0:3]
	v_mfma_f32_16x16x32_bf16 v[0:3], v[214:217], v[246:249], v[0:3]
	s_barrier
	s_add_i32 s58, s58, 2
	s_add_u32 s55, s55, 0x100000
	s_addc_u32 s57, s57, 0
	s_add_u32 s16, s16, 0x400000
	s_addc_u32 s17, s17, 0
	s_cmp_gt_u32 s58, 29
	s_cbranch_scc0 .LBB0_347
	s_and_b64 vcc, exec, s[68:69]
	s_cbranch_vccz .LBB0_350
	s_barrier

; #define PG8_STAGE(bufoff, gbase, voff) do { _Pragma("unroll") for (int _i = 0; _i < 2; ++_i) \
;         __builtin_amdgcn_global_load_lds((const unsigned*)((const char*)(gbase) + (voff)[_i]), (LAS unsigned*)(lds + (bufoff) + ldsw + _i * 8192), 16, 0, 0); } while (0)
; #define PG8_LDA(dst, b, h) do { _Pragma("unroll") for (int m = 0; m < 4; ++m) _Pragma("unroll") for (int k = 0; k < 2; ++k) dst[m][k] = *(const LAS bf16x8*)(lds + PG8_SA(b, h) + aoff + m * 2048 + k * 1024); } while (0)
; #define PG8_LDB(dst, b, h) do { _Pragma("unroll") for (int n = 0; n < 2; ++n) _Pragma("unroll") for (int k = 0; k < 2; ++k) dst[n][k] = *(const LAS bf16x8*)(lds + PG8_SB(b, h) + boff + n * 2048 + k * 1024); } while (0)
; #define PG8_MMA(ai, bj, At, Bt) do { __builtin_amdgcn_s_setprio(1); _Pragma("unroll") for (int m = 0; m < 4; ++m) _Pragma("unroll") for (int n = 0; n < 2; ++n) _Pragma("unroll") for (int k = 0; k < 2; ++k) \
;         acc[ai][bj][m][n] = __builtin_amdgcn_mfma_f32_16x16x32_bf16(Bt[n][k], At[m][k], acc[ai][bj][m][n], 0, 0, 0); __builtin_amdgcn_s_setprio(0); } while (0)
; #define PG8_WAIT_V(n) asm volatile("s_waitcnt vmcnt(" #n ")" ::: "memory")
; #define PG8_WAIT_L(n) asm volatile("s_waitcnt lgkmcnt(" #n ")" ::: "memory")
; template <bool ALIGN_EPI, class Epi, class Sched>
; __device__ __forceinline__ void gemm_phase(LAS unsigned char* lds, const int lda, const int ldb, const int K, const Sched& S, const Epi& E, const size_t kstepA = (size_t)(BK * 2), const size_t kstepB = (size_t)(BK * 2)) {
;     ...
;         for (int t = 0; t < nt; t += 2) {
;             const bool last = (t == nt - 2);
;             const char* a1 = cA + (size_t)(t + 1) * kstepA;
;             const char* a2 = last ? nA : cA + (size_t)(t + 2) * kstepA; const char* b2 = last ? nB : cB + (size_t)(t + 2) * kstep;
;             const char* a3 = a2 + kstepA; const char* b3 = b2 + kstep;
;             PG8_LDB(B0, 0, 0); PG8_LDB(B1, 0, 1); PG8_SCHED; PG8_LDA(At, 0, 0); PG8_STAGE(PG8_SA(1, 1), a1 + hstepA, voffA);
;             PG8_WAIT_V(8); PG8_WAIT_L(0); PG8_BAR; PG8_MMA(0, 0, At, B0); PG8_MMA(0, 1, At, B1); PG8_BAR; PG8_SCHED;
;             PG8_LDA(At, 0, 1); PG8_STAGE(PG8_SB(0, 0), b2, voffB); PG8_STAGE(PG8_SB(0, 1), b2 + hstepB, voffB); PG8_STAGE(PG8_SA(0, 0), a2, voffA);
;             PG8_WAIT_V(8); PG8_WAIT_L(0); PG8_BAR; PG8_MMA(1, 0, At, B0); PG8_MMA(1, 1, At, B1); PG8_BAR; PG8_SCHED;
.LBB0_726:
	ds_read_b128 v[88:91], v219
	ds_read_b128 v[92:95], v219 offset:1024
	ds_read_b128 v[112:115], v219 offset:2048
	ds_read_b128 v[116:119], v219 offset:3072
	ds_read_b128 v[144:147], v220
	ds_read_b128 v[148:151], v220 offset:1024
	ds_read_b128 v[152:155], v220 offset:2048
	ds_read_b128 v[156:159], v220 offset:3072
	s_add_u32 s14, s12, 0x1fc000
	s_addc_u32 s15, s13, 0
	s_cmp_eq_u32 s67, 28
	s_cselect_b32 s20, s0, s14
	s_cselect_b32 s21, s1, s15
	s_cselect_b32 s16, s6, s22
	s_cselect_b32 s17, s7, s23
	s_add_u32 s14, s20, 0x200000
	s_addc_u32 s15, s21, 0
	s_add_i32 m0, s19, 0xc000
	ds_read_b128 v[160:163], v221
	ds_read_b128 v[164:167], v221 offset:1024
	ds_read_b128 v[188:191], v221 offset:2048
	ds_read_b128 v[192:195], v221 offset:3072
	ds_read_b128 v[196:199], v221 offset:4096
	ds_read_b128 v[200:203], v221 offset:5120
	ds_read_b128 v[204:207], v221 offset:6144
	ds_read_b128 v[208:211], v221 offset:7168
	global_load_lds_dwordx4 v178, s[12:13]
	s_add_i32 m0, s19, 0xe000
	s_nop 0
	global_load_lds_dwordx4 v180, s[12:13]
	s_waitcnt vmcnt(8)
	s_waitcnt lgkmcnt(0)
	s_barrier
	s_waitcnt lgkmcnt(0)
	v_mfma_f32_16x16x32_bf16 v[140:143], v[88:91], v[160:163], v[140:143]
	v_mfma_f32_16x16x32_bf16 v[140:143], v[92:95], v[164:167], v[140:143]
	v_mfma_f32_16x16x32_bf16 v[124:127], v[88:91], v[188:191], v[124:127]
	v_mfma_f32_16x16x32_bf16 v[124:127], v[92:95], v[192:195], v[124:127]
	v_mfma_f32_16x16x32_bf16 v[100:103], v[88:91], v[196:199], v[100:103]
	v_mfma_f32_16x16x32_bf16 v[100:103], v[92:95], v[200:203], v[100:103]
	v_mfma_f32_16x16x32_bf16 v[76:79], v[88:91], v[204:207], v[76:79]
	v_mfma_f32_16x16x32_bf16 v[76:79], v[92:95], v[208:211], v[76:79]
	v_mfma_f32_16x16x32_bf16 v[136:139], v[112:115], v[160:163], v[136:139]
	v_mfma_f32_16x16x32_bf16 v[136:139], v[116:119], v[164:167], v[136:139]
	v_mfma_f32_16x16x32_bf16 v[120:123], v[112:115], v[188:191], v[120:123]
	v_mfma_f32_16x16x32_bf16 v[120:123], v[116:119], v[192:195], v[120:123]
	v_mfma_f32_16x16x32_bf16 v[96:99], v[112:115], v[196:199], v[96:99]
	v_mfma_f32_16x16x32_bf16 v[96:99], v[116:119], v[200:203], v[96:99]
	v_mfma_f32_16x16x32_bf16 v[72:75], v[112:115], v[204:207], v[72:75]
	v_mfma_f32_16x16x32_bf16 v[72:75], v[116:119], v[208:211], v[72:75]
	v_mfma_f32_16x16x32_bf16 v[132:135], v[144:147], v[160:163], v[132:135]
	v_mfma_f32_16x16x32_bf16 v[132:135], v[148:151], v[164:167], v[132:135]
	v_mfma_f32_16x16x32_bf16 v[108:111], v[144:147], v[188:191], v[108:111]
	v_mfma_f32_16x16x32_bf16 v[108:111], v[148:151], v[192:195], v[108:111]
	v_mfma_f32_16x16x32_bf16 v[84:87], v[144:147], v[196:199], v[84:87]
	v_mfma_f32_16x16x32_bf16 v[84:87], v[148:151], v[200:203], v[84:87]
	v_mfma_f32_16x16x32_bf16 v[68:71], v[144:147], v[204:207], v[68:71]
	v_mfma_f32_16x16x32_bf16 v[68:71], v[148:151], v[208:211], v[68:71]
	v_mfma_f32_16x16x32_bf16 v[128:131], v[152:155], v[160:163], v[128:131]
	v_mfma_f32_16x16x32_bf16 v[128:131], v[156:159], v[164:167], v[128:131]
	v_mfma_f32_16x16x32_bf16 v[104:107], v[152:155], v[188:191], v[104:107]
	v_mfma_f32_16x16x32_bf16 v[104:107], v[156:159], v[192:195], v[104:107]
	v_mfma_f32_16x16x32_bf16 v[80:83], v[152:155], v[196:199], v[80:83]
	v_mfma_f32_16x16x32_bf16 v[80:83], v[156:159], v[200:203], v[80:83]
	v_mfma_f32_16x16x32_bf16 v[64:67], v[152:155], v[204:207], v[64:67]
	v_mfma_f32_16x16x32_bf16 v[64:67], v[156:159], v[208:211], v[64:67]
	s_barrier
	s_add_i32 s69, s65, s18
	s_mov_b32 m0, s69
	ds_read_b128 v[160:163], v221 offset:16384
	ds_read_b128 v[164:167], v221 offset:17408
	ds_read_b128 v[188:191], v221 offset:18432
	ds_read_b128 v[192:195], v221 offset:19456
	ds_read_b128 v[196:199], v221 offset:20480
	ds_read_b128 v[200:203], v221 offset:21504
	ds_read_b128 v[204:207], v221 offset:22528
	ds_read_b128 v[208:211], v221 offset:23552
	global_load_lds_dwordx4 v170, s[16:17]
	s_add_i32 m0, s69, 0x2000
	s_add_u32 s78, s16, 0x4000
	s_addc_u32 s79, s17, 0
	s_add_i32 s69, s74, s18
	global_load_lds_dwordx4 v174, s[16:17]
	s_mov_b32 m0, s69
	s_nop 0
	global_load_lds_dwordx4 v170, s[78:79]
	s_add_i32 m0, s69, 0x2000
	s_nop 0
	global_load_lds_dwordx4 v174, s[78:79]
	s_mov_b32 m0, s19
	s_nop 0
	global_load_lds_dwordx4 v168, s[20:21]
	s_mov_b32 m0, s30
	s_nop 0
	global_load_lds_dwordx4 v172, s[20:21]
	s_waitcnt vmcnt(8)
	s_waitcnt lgkmcnt(0)
	s_barrier
	s_waitcnt lgkmcnt(0)
	v_mfma_f32_16x16x32_bf16 v[60:63], v[88:91], v[160:163], v[60:63]
	v_mfma_f32_16x16x32_bf16 v[60:63], v[92:95], v[164:167], v[60:63]
	v_mfma_f32_16x16x32_bf16 v[44:47], v[88:91], v[188:191], v[44:47]
	v_mfma_f32_16x16x32_bf16 v[44:47], v[92:95], v[192:195], v[44:47]
	v_mfma_f32_16x16x32_bf16 v[28:31], v[88:91], v[196:199], v[28:31]
	v_mfma_f32_16x16x32_bf16 v[28:31], v[92:95], v[200:203], v[28:31]
	v_mfma_f32_16x16x32_bf16 v[12:15], v[88:91], v[204:207], v[12:15]
	v_mfma_f32_16x16x32_bf16 v[12:15], v[92:95], v[208:211], v[12:15]
	v_mfma_f32_16x16x32_bf16 v[56:59], v[112:115], v[160:163], v[56:59]
	v_mfma_f32_16x16x32_bf16 v[56:59], v[116:119], v[164:167], v[56:59]
	v_mfma_f32_16x16x32_bf16 v[40:43], v[112:115], v[188:191], v[40:43]
	v_mfma_f32_16x16x32_bf16 v[40:43], v[116:119], v[192:195], v[40:43]
	v_mfma_f32_16x16x32_bf16 v[24:27], v[112:115], v[196:199], v[24:27]
	v_mfma_f32_16x16x32_bf16 v[24:27], v[116:119], v[200:203], v[24:27]
	v_mfma_f32_16x16x32_bf16 v[8:11], v[112:115], v[204:207], v[8:11]
	v_mfma_f32_16x16x32_bf16 v[8:11], v[116:119], v[208:211], v[8:11]
	v_mfma_f32_16x16x32_bf16 v[52:55], v[144:147], v[160:163], v[52:55]
	v_mfma_f32_16x16x32_bf16 v[52:55], v[148:151], v[164:167], v[52:55]
	v_mfma_f32_16x16x32_bf16 v[36:39], v[144:147], v[188:191], v[36:39]
	v_mfma_f32_16x16x32_bf16 v[36:39], v[148:151], v[192:195], v[36:39]
	v_mfma_f32_16x16x32_bf16 v[20:23], v[144:147], v[196:199], v[20:23]
	v_mfma_f32_16x16x32_bf16 v[20:23], v[148:151], v[200:203], v[20:23]
	v_mfma_f32_16x16x32_bf16 v[4:7], v[144:147], v[204:207], v[4:7]
	v_mfma_f32_16x16x32_bf16 v[4:7], v[148:151], v[208:211], v[4:7]
	v_mfma_f32_16x16x32_bf16 v[48:51], v[152:155], v[160:163], v[48:51]
	v_mfma_f32_16x16x32_bf16 v[48:51], v[156:159], v[164:167], v[48:51]
	v_mfma_f32_16x16x32_bf16 v[32:35], v[152:155], v[188:191], v[32:35]
	v_mfma_f32_16x16x32_bf16 v[32:35], v[156:159], v[192:195], v[32:35]
	v_mfma_f32_16x16x32_bf16 v[16:19], v[152:155], v[196:199], v[16:19]
	v_mfma_f32_16x16x32_bf16 v[16:19], v[156:159], v[200:203], v[16:19]
	v_mfma_f32_16x16x32_bf16 v[0:3], v[152:155], v[204:207], v[0:3]
	v_mfma_f32_16x16x32_bf16 v[0:3], v[156:159], v[208:211], v[0:3]
	s_barrier
; #define PG8_STAGE(bufoff, gbase, voff) do { _Pragma("unroll") for (int _i = 0; _i < 2; ++_i) \
;         __builtin_amdgcn_global_load_lds((const unsigned*)((const char*)(gbase) + (voff)[_i]), (LAS unsigned*)(lds + (bufoff) + ldsw + _i * 8192), 16, 0, 0); } while (0)
; #define PG8_LDA(dst, b, h) do { _Pragma("unroll") for (int m = 0; m < 4; ++m) _Pragma("unroll") for (int k = 0; k < 2; ++k) dst[m][k] = *(const LAS bf16x8*)(lds + PG8_SA(b, h) + aoff + m * 2048 + k * 1024); } while (0)
; #define PG8_LDB(dst, b, h) do { _Pragma("unroll") for (int n = 0; n < 2; ++n) _Pragma("unroll") for (int k = 0; k < 2; ++k) dst[n][k] = *(const LAS bf16x8*)(lds + PG8_SB(b, h) + boff + n * 2048 + k * 1024); } while (0)
; #define PG8_MMA(ai, bj, At, Bt) do { __builtin_amdgcn_s_setprio(1); _Pragma("unroll") for (int m = 0; m < 4; ++m) _Pragma("unroll") for (int n = 0; n < 2; ++n) _Pragma("unroll") for (int k = 0; k < 2; ++k) \
;         acc[ai][bj][m][n] = __builtin_amdgcn_mfma_f32_16x16x32_bf16(Bt[n][k], At[m][k], acc[ai][bj][m][n], 0, 0, 0); __builtin_amdgcn_s_setprio(0); } while (0)
; #define PG8_WAIT_V(n) asm volatile("s_waitcnt vmcnt(" #n ")" ::: "memory")
; #define PG8_WAIT_L(n) asm volatile("s_waitcnt lgkmcnt(" #n ")" ::: "memory")
; #define PG8_BAR __builtin_amdgcn_s_barrier()
; #define PG8_SCHED __builtin_amdgcn_sched_barrier(0)
; template <bool ALIGN_EPI, class Epi, class Sched>
; __device__ __forceinline__ void gemm_phase(LAS unsigned char* lds, const int lda, const int ldb, const int K, const Sched& S, const Epi& E, const size_t kstepA = (size_t)(BK * 2), const size_t kstepB = (size_t)(BK * 2)) {
;     ...
;             PG8_LDB(B0, 1, 0); PG8_LDB(B1, 1, 1); PG8_SCHED; PG8_LDA(At, 1, 0); PG8_STAGE(PG8_SA(0, 1), a2 + hstepA, voffA);
;             PG8_WAIT_V(8); PG8_WAIT_L(0); PG8_BAR; PG8_MMA(0, 0, At, B0); PG8_MMA(0, 1, At, B1); PG8_BAR; PG8_SCHED;
;             PG8_LDA(At, 1, 1); PG8_STAGE(PG8_SB(1, 0), b3, voffB); PG8_STAGE(PG8_SB(1, 1), b3 + hstepB, voffB); PG8_STAGE(PG8_SA(1, 0), a3, voffA);
;             PG8_WAIT_V(8); PG8_WAIT_L(0); PG8_BAR; PG8_MMA(1, 0, At, B0); PG8_MMA(1, 1, At, B1); PG8_BAR; PG8_SCHED;
;         }
	s_add_i32 s69, 0, 0x18000
	s_add_i32 s77, 0, 0x1c000
	v_add_u32_e32 v116, s69, v218
	v_add_u32_e32 v156, s77, v218
	ds_read_b128 v[88:91], v116
	ds_read_b128 v[92:95], v116 offset:1024
	ds_read_b128 v[112:115], v116 offset:2048
	ds_read_b128 v[116:119], v116 offset:3072
	ds_read_b128 v[144:147], v156
	ds_read_b128 v[148:151], v156 offset:1024
	ds_read_b128 v[152:155], v156 offset:2048
	ds_read_b128 v[156:159], v156 offset:3072
	s_add_u32 s20, s20, 0x4000
	s_addc_u32 s21, s21, 0
	s_mov_b32 m0, s33
	ds_read_b128 v[160:163], v221 offset:32768
	ds_read_b128 v[164:167], v221 offset:33792
	ds_read_b128 v[188:191], v221 offset:34816
	ds_read_b128 v[192:195], v221 offset:35840
	ds_read_b128 v[196:199], v221 offset:36864
	ds_read_b128 v[200:203], v221 offset:37888
	ds_read_b128 v[204:207], v221 offset:38912
	ds_read_b128 v[208:211], v221 offset:39936
	global_load_lds_dwordx4 v168, s[20:21]
	s_mov_b32 m0, s42
	s_nop 0
	global_load_lds_dwordx4 v172, s[20:21]
	s_waitcnt vmcnt(8)
	s_waitcnt lgkmcnt(0)
	s_barrier
	s_waitcnt lgkmcnt(0)
	v_mfma_f32_16x16x32_bf16 v[140:143], v[88:91], v[160:163], v[140:143]
	v_mfma_f32_16x16x32_bf16 v[140:143], v[92:95], v[164:167], v[140:143]
	v_mfma_f32_16x16x32_bf16 v[124:127], v[88:91], v[188:191], v[124:127]
	v_mfma_f32_16x16x32_bf16 v[124:127], v[92:95], v[192:195], v[124:127]
	v_mfma_f32_16x16x32_bf16 v[100:103], v[88:91], v[196:199], v[100:103]
	v_mfma_f32_16x16x32_bf16 v[100:103], v[92:95], v[200:203], v[100:103]
	v_mfma_f32_16x16x32_bf16 v[76:79], v[88:91], v[204:207], v[76:79]
	v_mfma_f32_16x16x32_bf16 v[76:79], v[92:95], v[208:211], v[76:79]
	v_mfma_f32_16x16x32_bf16 v[136:139], v[112:115], v[160:163], v[136:139]
	v_mfma_f32_16x16x32_bf16 v[136:139], v[116:119], v[164:167], v[136:139]
	v_mfma_f32_16x16x32_bf16 v[120:123], v[112:115], v[188:191], v[120:123]
	v_mfma_f32_16x16x32_bf16 v[120:123], v[116:119], v[192:195], v[120:123]
	v_mfma_f32_16x16x32_bf16 v[96:99], v[112:115], v[196:199], v[96:99]
	v_mfma_f32_16x16x32_bf16 v[96:99], v[116:119], v[200:203], v[96:99]
	v_mfma_f32_16x16x32_bf16 v[72:75], v[112:115], v[204:207], v[72:75]
	v_mfma_f32_16x16x32_bf16 v[72:75], v[116:119], v[208:211], v[72:75]
	v_mfma_f32_16x16x32_bf16 v[132:135], v[144:147], v[160:163], v[132:135]
	v_mfma_f32_16x16x32_bf16 v[132:135], v[148:151], v[164:167], v[132:135]
	v_mfma_f32_16x16x32_bf16 v[108:111], v[144:147], v[188:191], v[108:111]
	v_mfma_f32_16x16x32_bf16 v[108:111], v[148:151], v[192:195], v[108:111]
	v_mfma_f32_16x16x32_bf16 v[84:87], v[144:147], v[196:199], v[84:87]
	v_mfma_f32_16x16x32_bf16 v[84:87], v[148:151], v[200:203], v[84:87]
	v_mfma_f32_16x16x32_bf16 v[68:71], v[144:147], v[204:207], v[68:71]
	v_mfma_f32_16x16x32_bf16 v[68:71], v[148:151], v[208:211], v[68:71]
	v_mfma_f32_16x16x32_bf16 v[128:131], v[152:155], v[160:163], v[128:131]
	v_mfma_f32_16x16x32_bf16 v[128:131], v[156:159], v[164:167], v[128:131]
	v_mfma_f32_16x16x32_bf16 v[104:107], v[152:155], v[188:191], v[104:107]
	v_mfma_f32_16x16x32_bf16 v[104:107], v[156:159], v[192:195], v[104:107]
	v_mfma_f32_16x16x32_bf16 v[80:83], v[152:155], v[196:199], v[80:83]
	v_mfma_f32_16x16x32_bf16 v[80:83], v[156:159], v[200:203], v[80:83]
	v_mfma_f32_16x16x32_bf16 v[64:67], v[152:155], v[204:207], v[64:67]
	v_mfma_f32_16x16x32_bf16 v[64:67], v[156:159], v[208:211], v[64:67]
	s_barrier
	s_add_u32 s20, s16, 0x40000
	s_addc_u32 s21, s17, 0
	s_add_i32 s69, s69, s18
	s_mov_b32 m0, s69
	ds_read_b128 v[160:163], v221 offset:49152
	ds_read_b128 v[164:167], v221 offset:50176
	ds_read_b128 v[188:191], v221 offset:51200
	ds_read_b128 v[192:195], v221 offset:52224
	ds_read_b128 v[196:199], v221 offset:53248
	ds_read_b128 v[200:203], v221 offset:54272
	ds_read_b128 v[204:207], v221 offset:55296
	ds_read_b128 v[208:211], v221 offset:56320
	global_load_lds_dwordx4 v170, s[20:21]
	s_add_i32 m0, s69, 0x2000
	s_add_u32 s16, s16, 0x44000
	global_load_lds_dwordx4 v174, s[20:21]
	s_addc_u32 s17, s17, 0
	s_add_i32 s20, s77, s18
	s_mov_b32 m0, s20
	s_nop 0
	global_load_lds_dwordx4 v170, s[16:17]
	s_add_i32 m0, s20, 0x2000
	s_nop 0
	global_load_lds_dwordx4 v174, s[16:17]
	s_mov_b32 m0, s51
	s_nop 0
	global_load_lds_dwordx4 v168, s[14:15]
	s_mov_b32 m0, s64
	s_nop 0
	global_load_lds_dwordx4 v172, s[14:15]
	s_waitcnt vmcnt(8)
	s_waitcnt lgkmcnt(0)
	s_barrier
	s_waitcnt lgkmcnt(0)
	v_mfma_f32_16x16x32_bf16 v[60:63], v[88:91], v[160:163], v[60:63]
	v_mfma_f32_16x16x32_bf16 v[60:63], v[92:95], v[164:167], v[60:63]
	v_mfma_f32_16x16x32_bf16 v[44:47], v[88:91], v[188:191], v[44:47]
	v_mfma_f32_16x16x32_bf16 v[44:47], v[92:95], v[192:195], v[44:47]
	v_mfma_f32_16x16x32_bf16 v[28:31], v[88:91], v[196:199], v[28:31]
	v_mfma_f32_16x16x32_bf16 v[28:31], v[92:95], v[200:203], v[28:31]
	v_mfma_f32_16x16x32_bf16 v[12:15], v[88:91], v[204:207], v[12:15]
	v_mfma_f32_16x16x32_bf16 v[12:15], v[92:95], v[208:211], v[12:15]
	v_mfma_f32_16x16x32_bf16 v[56:59], v[112:115], v[160:163], v[56:59]
	v_mfma_f32_16x16x32_bf16 v[56:59], v[116:119], v[164:167], v[56:59]
	v_mfma_f32_16x16x32_bf16 v[40:43], v[112:115], v[188:191], v[40:43]
	v_mfma_f32_16x16x32_bf16 v[40:43], v[116:119], v[192:195], v[40:43]
	v_mfma_f32_16x16x32_bf16 v[24:27], v[112:115], v[196:199], v[24:27]
	v_mfma_f32_16x16x32_bf16 v[24:27], v[116:119], v[200:203], v[24:27]
	v_mfma_f32_16x16x32_bf16 v[8:11], v[112:115], v[204:207], v[8:11]
	v_mfma_f32_16x16x32_bf16 v[8:11], v[116:119], v[208:211], v[8:11]
	v_mfma_f32_16x16x32_bf16 v[52:55], v[144:147], v[160:163], v[52:55]
	v_mfma_f32_16x16x32_bf16 v[52:55], v[148:151], v[164:167], v[52:55]
	v_mfma_f32_16x16x32_bf16 v[36:39], v[144:147], v[188:191], v[36:39]
	v_mfma_f32_16x16x32_bf16 v[36:39], v[148:151], v[192:195], v[36:39]
	v_mfma_f32_16x16x32_bf16 v[20:23], v[144:147], v[196:199], v[20:23]
	v_mfma_f32_16x16x32_bf16 v[20:23], v[148:151], v[200:203], v[20:23]
	v_mfma_f32_16x16x32_bf16 v[4:7], v[144:147], v[204:207], v[4:7]
	v_mfma_f32_16x16x32_bf16 v[4:7], v[148:151], v[208:211], v[4:7]
	v_mfma_f32_16x16x32_bf16 v[48:51], v[152:155], v[160:163], v[48:51]
	v_mfma_f32_16x16x32_bf16 v[48:51], v[156:159], v[164:167], v[48:51]
	v_mfma_f32_16x16x32_bf16 v[32:35], v[152:155], v[188:191], v[32:35]
	v_mfma_f32_16x16x32_bf16 v[32:35], v[156:159], v[192:195], v[32:35]
	v_mfma_f32_16x16x32_bf16 v[16:19], v[152:155], v[196:199], v[16:19]
	v_mfma_f32_16x16x32_bf16 v[16:19], v[156:159], v[200:203], v[16:19]
	v_mfma_f32_16x16x32_bf16 v[0:3], v[152:155], v[204:207], v[0:3]
	v_mfma_f32_16x16x32_bf16 v[0:3], v[156:159], v[208:211], v[0:3]
	s_barrier
	s_add_i32 s67, s67, 2
	s_add_u32 s22, s22, 0x80000
	s_addc_u32 s23, s23, 0
	s_add_u32 s12, s12, 0x400000
	s_addc_u32 s13, s13, 0
	s_cmp_gt_u32 s67, 29
	s_cbranch_scc0 .LBB0_726
	s_and_b64 vcc, exec, s[56:57]
	s_cbranch_vccz .LBB0_729
	s_barrier

; #define PG8_STAGE(bufoff, gbase, voff) do { _Pragma("unroll") for (int _i = 0; _i < 2; ++_i) \
;         __builtin_amdgcn_global_load_lds((const unsigned*)((const char*)(gbase) + (voff)[_i]), (LAS unsigned*)(lds + (bufoff) + ldsw + _i * 8192), 16, 0, 0); } while (0)
; #define PG8_LDA(dst, b, h) do { _Pragma("unroll") for (int m = 0; m < 4; ++m) _Pragma("unroll") for (int k = 0; k < 2; ++k) dst[m][k] = *(const LAS bf16x8*)(lds + PG8_SA(b, h) + aoff + m * 2048 + k * 1024); } while (0)
; #define PG8_LDB(dst, b, h) do { _Pragma("unroll") for (int n = 0; n < 2; ++n) _Pragma("unroll") for (int k = 0; k < 2; ++k) dst[n][k] = *(const LAS bf16x8*)(lds + PG8_SB(b, h) + boff + n * 2048 + k * 1024); } while (0)
; #define PG8_MMA(ai, bj, At, Bt) do { __builtin_amdgcn_s_setprio(1); _Pragma("unroll") for (int m = 0; m < 4; ++m) _Pragma("unroll") for (int n = 0; n < 2; ++n) _Pragma("unroll") for (int k = 0; k < 2; ++k) \
;         acc[ai][bj][m][n] = __builtin_amdgcn_mfma_f32_16x16x32_bf16(Bt[n][k], At[m][k], acc[ai][bj][m][n], 0, 0, 0); __builtin_amdgcn_s_setprio(0); } while (0)
; #define PG8_WAIT_V(n) asm volatile("s_waitcnt vmcnt(" #n ")" ::: "memory")
; #define PG8_WAIT_L(n) asm volatile("s_waitcnt lgkmcnt(" #n ")" ::: "memory")
; template <bool ALIGN_EPI, class Epi, class Sched>
; __device__ __forceinline__ void gemm_phase(LAS unsigned char* lds, const int lda, const int ldb, const int K, const Sched& S, const Epi& E, const size_t kstepA = (size_t)(BK * 2), const size_t kstepB = (size_t)(BK * 2)) {
;     ...
;         for (int t = 0; t < nt; t += 2) {
;             const bool last = (t == nt - 2);
;             const char* a1 = cA + (size_t)(t + 1) * kstepA;
;             const char* a2 = last ? nA : cA + (size_t)(t + 2) * kstepA; const char* b2 = last ? nB : cB + (size_t)(t + 2) * kstep;
;             const char* a3 = a2 + kstepA; const char* b3 = b2 + kstep;
;             PG8_LDB(B0, 0, 0); PG8_LDB(B1, 0, 1); PG8_SCHED; PG8_LDA(At, 0, 0); PG8_STAGE(PG8_SA(1, 1), a1 + hstepA, voffA);
;             PG8_WAIT_V(8); PG8_WAIT_L(0); PG8_BAR; PG8_MMA(0, 0, At, B0); PG8_MMA(0, 1, At, B1); PG8_BAR; PG8_SCHED;
;             PG8_LDA(At, 0, 1); PG8_STAGE(PG8_SB(0, 0), b2, voffB); PG8_STAGE(PG8_SB(0, 1), b2 + hstepB, voffB); PG8_STAGE(PG8_SA(0, 0), a2, voffA);
;             PG8_WAIT_V(8); PG8_WAIT_L(0); PG8_BAR; PG8_MMA(1, 0, At, B0); PG8_MMA(1, 1, At, B1); PG8_BAR; PG8_SCHED;
.LBB0_952:
	ds_read_b128 v[88:91], v219
	ds_read_b128 v[92:95], v219 offset:1024
	ds_read_b128 v[112:115], v219 offset:2048
	ds_read_b128 v[116:119], v219 offset:3072
	ds_read_b128 v[144:147], v220
	ds_read_b128 v[148:151], v220 offset:1024
	ds_read_b128 v[152:155], v220 offset:2048
	ds_read_b128 v[156:159], v220 offset:3072
	s_add_u32 s14, s12, 0x1fc000
	s_addc_u32 s15, s13, 0
	s_cmp_eq_u32 s61, 12
	s_cselect_b32 s20, s0, s14
	s_cselect_b32 s21, s1, s15
	s_cselect_b32 s16, s6, s22
	s_cselect_b32 s17, s7, s23
	s_add_u32 s14, s20, 0x200000
	s_addc_u32 s15, s21, 0
	s_add_i32 m0, s19, 0xc000
	ds_read_b128 v[160:163], v221
	ds_read_b128 v[164:167], v221 offset:1024
	ds_read_b128 v[188:191], v221 offset:2048
	ds_read_b128 v[192:195], v221 offset:3072
	ds_read_b128 v[196:199], v221 offset:4096
	ds_read_b128 v[200:203], v221 offset:5120
	ds_read_b128 v[204:207], v221 offset:6144
	ds_read_b128 v[208:211], v221 offset:7168
	global_load_lds_dwordx4 v178, s[12:13]
	s_add_i32 m0, s19, 0xe000
	s_nop 0
	global_load_lds_dwordx4 v180, s[12:13]
	s_waitcnt vmcnt(8)
	s_waitcnt lgkmcnt(0)
	s_barrier
	s_waitcnt lgkmcnt(0)
	v_mfma_f32_16x16x32_bf16 v[140:143], v[88:91], v[160:163], v[140:143]
	v_mfma_f32_16x16x32_bf16 v[140:143], v[92:95], v[164:167], v[140:143]
	v_mfma_f32_16x16x32_bf16 v[124:127], v[88:91], v[188:191], v[124:127]
	v_mfma_f32_16x16x32_bf16 v[124:127], v[92:95], v[192:195], v[124:127]
	v_mfma_f32_16x16x32_bf16 v[100:103], v[88:91], v[196:199], v[100:103]
	v_mfma_f32_16x16x32_bf16 v[100:103], v[92:95], v[200:203], v[100:103]
	v_mfma_f32_16x16x32_bf16 v[76:79], v[88:91], v[204:207], v[76:79]
	v_mfma_f32_16x16x32_bf16 v[76:79], v[92:95], v[208:211], v[76:79]
	v_mfma_f32_16x16x32_bf16 v[136:139], v[112:115], v[160:163], v[136:139]
	v_mfma_f32_16x16x32_bf16 v[136:139], v[116:119], v[164:167], v[136:139]
	v_mfma_f32_16x16x32_bf16 v[120:123], v[112:115], v[188:191], v[120:123]
	v_mfma_f32_16x16x32_bf16 v[120:123], v[116:119], v[192:195], v[120:123]
	v_mfma_f32_16x16x32_bf16 v[96:99], v[112:115], v[196:199], v[96:99]
	v_mfma_f32_16x16x32_bf16 v[96:99], v[116:119], v[200:203], v[96:99]
	v_mfma_f32_16x16x32_bf16 v[72:75], v[112:115], v[204:207], v[72:75]
	v_mfma_f32_16x16x32_bf16 v[72:75], v[116:119], v[208:211], v[72:75]
	v_mfma_f32_16x16x32_bf16 v[132:135], v[144:147], v[160:163], v[132:135]
	v_mfma_f32_16x16x32_bf16 v[132:135], v[148:151], v[164:167], v[132:135]
	v_mfma_f32_16x16x32_bf16 v[108:111], v[144:147], v[188:191], v[108:111]
	v_mfma_f32_16x16x32_bf16 v[108:111], v[148:151], v[192:195], v[108:111]
	v_mfma_f32_16x16x32_bf16 v[84:87], v[144:147], v[196:199], v[84:87]
	v_mfma_f32_16x16x32_bf16 v[84:87], v[148:151], v[200:203], v[84:87]
	v_mfma_f32_16x16x32_bf16 v[68:71], v[144:147], v[204:207], v[68:71]
	v_mfma_f32_16x16x32_bf16 v[68:71], v[148:151], v[208:211], v[68:71]
	v_mfma_f32_16x16x32_bf16 v[128:131], v[152:155], v[160:163], v[128:131]
	v_mfma_f32_16x16x32_bf16 v[128:131], v[156:159], v[164:167], v[128:131]
	v_mfma_f32_16x16x32_bf16 v[104:107], v[152:155], v[188:191], v[104:107]
	v_mfma_f32_16x16x32_bf16 v[104:107], v[156:159], v[192:195], v[104:107]
	v_mfma_f32_16x16x32_bf16 v[80:83], v[152:155], v[196:199], v[80:83]
	v_mfma_f32_16x16x32_bf16 v[80:83], v[156:159], v[200:203], v[80:83]
	v_mfma_f32_16x16x32_bf16 v[64:67], v[152:155], v[204:207], v[64:67]
	v_mfma_f32_16x16x32_bf16 v[64:67], v[156:159], v[208:211], v[64:67]
	s_barrier
	s_add_i32 s63, s71, s18
	s_mov_b32 m0, s63
	ds_read_b128 v[160:163], v221 offset:16384
	ds_read_b128 v[164:167], v221 offset:17408
	ds_read_b128 v[188:191], v221 offset:18432
	ds_read_b128 v[192:195], v221 offset:19456
	ds_read_b128 v[196:199], v221 offset:20480
	ds_read_b128 v[200:203], v221 offset:21504
	ds_read_b128 v[204:207], v221 offset:22528
	ds_read_b128 v[208:211], v221 offset:23552
	global_load_lds_dwordx4 v170, s[16:17]
	s_add_i32 m0, s63, 0x2000
	s_add_u32 s76, s16, 0x4000
	s_addc_u32 s77, s17, 0
	s_add_i32 s63, s72, s18
	global_load_lds_dwordx4 v174, s[16:17]
	s_mov_b32 m0, s63
	s_nop 0
	global_load_lds_dwordx4 v170, s[76:77]
	s_add_i32 m0, s63, 0x2000
	s_nop 0
	global_load_lds_dwordx4 v174, s[76:77]
	s_mov_b32 m0, s19
	s_nop 0
	global_load_lds_dwordx4 v168, s[20:21]
	s_mov_b32 m0, s33
	s_nop 0
	global_load_lds_dwordx4 v172, s[20:21]
	s_waitcnt vmcnt(8)
	s_waitcnt lgkmcnt(0)
	s_barrier
	s_waitcnt lgkmcnt(0)
	v_mfma_f32_16x16x32_bf16 v[60:63], v[88:91], v[160:163], v[60:63]
	v_mfma_f32_16x16x32_bf16 v[60:63], v[92:95], v[164:167], v[60:63]
	v_mfma_f32_16x16x32_bf16 v[44:47], v[88:91], v[188:191], v[44:47]
	v_mfma_f32_16x16x32_bf16 v[44:47], v[92:95], v[192:195], v[44:47]
	v_mfma_f32_16x16x32_bf16 v[28:31], v[88:91], v[196:199], v[28:31]
	v_mfma_f32_16x16x32_bf16 v[28:31], v[92:95], v[200:203], v[28:31]
	v_mfma_f32_16x16x32_bf16 v[12:15], v[88:91], v[204:207], v[12:15]
	v_mfma_f32_16x16x32_bf16 v[12:15], v[92:95], v[208:211], v[12:15]
	v_mfma_f32_16x16x32_bf16 v[56:59], v[112:115], v[160:163], v[56:59]
	v_mfma_f32_16x16x32_bf16 v[56:59], v[116:119], v[164:167], v[56:59]
	v_mfma_f32_16x16x32_bf16 v[40:43], v[112:115], v[188:191], v[40:43]
	v_mfma_f32_16x16x32_bf16 v[40:43], v[116:119], v[192:195], v[40:43]
	v_mfma_f32_16x16x32_bf16 v[24:27], v[112:115], v[196:199], v[24:27]
	v_mfma_f32_16x16x32_bf16 v[24:27], v[116:119], v[200:203], v[24:27]
	v_mfma_f32_16x16x32_bf16 v[8:11], v[112:115], v[204:207], v[8:11]
	v_mfma_f32_16x16x32_bf16 v[8:11], v[116:119], v[208:211], v[8:11]
	v_mfma_f32_16x16x32_bf16 v[52:55], v[144:147], v[160:163], v[52:55]
	v_mfma_f32_16x16x32_bf16 v[52:55], v[148:151], v[164:167], v[52:55]
	v_mfma_f32_16x16x32_bf16 v[36:39], v[144:147], v[188:191], v[36:39]
	v_mfma_f32_16x16x32_bf16 v[36:39], v[148:151], v[192:195], v[36:39]
	v_mfma_f32_16x16x32_bf16 v[20:23], v[144:147], v[196:199], v[20:23]
	v_mfma_f32_16x16x32_bf16 v[20:23], v[148:151], v[200:203], v[20:23]
	v_mfma_f32_16x16x32_bf16 v[4:7], v[144:147], v[204:207], v[4:7]
	v_mfma_f32_16x16x32_bf16 v[4:7], v[148:151], v[208:211], v[4:7]
	v_mfma_f32_16x16x32_bf16 v[48:51], v[152:155], v[160:163], v[48:51]
	v_mfma_f32_16x16x32_bf16 v[48:51], v[156:159], v[164:167], v[48:51]
	v_mfma_f32_16x16x32_bf16 v[32:35], v[152:155], v[188:191], v[32:35]
	v_mfma_f32_16x16x32_bf16 v[32:35], v[156:159], v[192:195], v[32:35]
	v_mfma_f32_16x16x32_bf16 v[16:19], v[152:155], v[196:199], v[16:19]
	v_mfma_f32_16x16x32_bf16 v[16:19], v[156:159], v[200:203], v[16:19]
	v_mfma_f32_16x16x32_bf16 v[0:3], v[152:155], v[204:207], v[0:3]
	v_mfma_f32_16x16x32_bf16 v[0:3], v[156:159], v[208:211], v[0:3]
	s_barrier
; #define PG8_STAGE(bufoff, gbase, voff) do { _Pragma("unroll") for (int _i = 0; _i < 2; ++_i) \
;         __builtin_amdgcn_global_load_lds((const unsigned*)((const char*)(gbase) + (voff)[_i]), (LAS unsigned*)(lds + (bufoff) + ldsw + _i * 8192), 16, 0, 0); } while (0)
; #define PG8_LDA(dst, b, h) do { _Pragma("unroll") for (int m = 0; m < 4; ++m) _Pragma("unroll") for (int k = 0; k < 2; ++k) dst[m][k] = *(const LAS bf16x8*)(lds + PG8_SA(b, h) + aoff + m * 2048 + k * 1024); } while (0)
; #define PG8_LDB(dst, b, h) do { _Pragma("unroll") for (int n = 0; n < 2; ++n) _Pragma("unroll") for (int k = 0; k < 2; ++k) dst[n][k] = *(const LAS bf16x8*)(lds + PG8_SB(b, h) + boff + n * 2048 + k * 1024); } while (0)
; #define PG8_MMA(ai, bj, At, Bt) do { __builtin_amdgcn_s_setprio(1); _Pragma("unroll") for (int m = 0; m < 4; ++m) _Pragma("unroll") for (int n = 0; n < 2; ++n) _Pragma("unroll") for (int k = 0; k < 2; ++k) \
;         acc[ai][bj][m][n] = __builtin_amdgcn_mfma_f32_16x16x32_bf16(Bt[n][k], At[m][k], acc[ai][bj][m][n], 0, 0, 0); __builtin_amdgcn_s_setprio(0); } while (0)
; #define PG8_WAIT_V(n) asm volatile("s_waitcnt vmcnt(" #n ")" ::: "memory")
; #define PG8_WAIT_L(n) asm volatile("s_waitcnt lgkmcnt(" #n ")" ::: "memory")
; #define PG8_BAR __builtin_amdgcn_s_barrier()
; #define PG8_SCHED __builtin_amdgcn_sched_barrier(0)
; template <bool ALIGN_EPI, class Epi, class Sched>
; __device__ __forceinline__ void gemm_phase(LAS unsigned char* lds, const int lda, const int ldb, const int K, const Sched& S, const Epi& E, const size_t kstepA = (size_t)(BK * 2), const size_t kstepB = (size_t)(BK * 2)) {
;     ...
;             PG8_LDB(B0, 1, 0); PG8_LDB(B1, 1, 1); PG8_SCHED; PG8_LDA(At, 1, 0); PG8_STAGE(PG8_SA(0, 1), a2 + hstepA, voffA);
;             PG8_WAIT_V(8); PG8_WAIT_L(0); PG8_BAR; PG8_MMA(0, 0, At, B0); PG8_MMA(0, 1, At, B1); PG8_BAR; PG8_SCHED;
;             PG8_LDA(At, 1, 1); PG8_STAGE(PG8_SB(1, 0), b3, voffB); PG8_STAGE(PG8_SB(1, 1), b3 + hstepB, voffB); PG8_STAGE(PG8_SA(1, 0), a3, voffA);
;             PG8_WAIT_V(8); PG8_WAIT_L(0); PG8_BAR; PG8_MMA(1, 0, At, B0); PG8_MMA(1, 1, At, B1); PG8_BAR; PG8_SCHED;
;         }
	s_add_i32 s63, 0, 0x18000
	s_add_i32 s75, 0, 0x1c000
	v_add_u32_e32 v116, s63, v218
	v_add_u32_e32 v156, s75, v218
	ds_read_b128 v[88:91], v116
	ds_read_b128 v[92:95], v116 offset:1024
	ds_read_b128 v[112:115], v116 offset:2048
	ds_read_b128 v[116:119], v116 offset:3072
	ds_read_b128 v[144:147], v156
	ds_read_b128 v[148:151], v156 offset:1024
	ds_read_b128 v[152:155], v156 offset:2048
	ds_read_b128 v[156:159], v156 offset:3072
	s_add_u32 s20, s20, 0x4000
	s_addc_u32 s21, s21, 0
	s_mov_b32 m0, s42
	ds_read_b128 v[160:163], v221 offset:32768
	ds_read_b128 v[164:167], v221 offset:33792
	ds_read_b128 v[188:191], v221 offset:34816
	ds_read_b128 v[192:195], v221 offset:35840
	ds_read_b128 v[196:199], v221 offset:36864
	ds_read_b128 v[200:203], v221 offset:37888
	ds_read_b128 v[204:207], v221 offset:38912
	ds_read_b128 v[208:211], v221 offset:39936
	global_load_lds_dwordx4 v168, s[20:21]
	s_mov_b32 m0, s43
	s_nop 0
	global_load_lds_dwordx4 v172, s[20:21]
	s_waitcnt vmcnt(8)
	s_waitcnt lgkmcnt(0)
	s_barrier
	s_waitcnt lgkmcnt(0)
	v_mfma_f32_16x16x32_bf16 v[140:143], v[88:91], v[160:163], v[140:143]
	v_mfma_f32_16x16x32_bf16 v[140:143], v[92:95], v[164:167], v[140:143]
	v_mfma_f32_16x16x32_bf16 v[124:127], v[88:91], v[188:191], v[124:127]
	v_mfma_f32_16x16x32_bf16 v[124:127], v[92:95], v[192:195], v[124:127]
	v_mfma_f32_16x16x32_bf16 v[100:103], v[88:91], v[196:199], v[100:103]
	v_mfma_f32_16x16x32_bf16 v[100:103], v[92:95], v[200:203], v[100:103]
	v_mfma_f32_16x16x32_bf16 v[76:79], v[88:91], v[204:207], v[76:79]
	v_mfma_f32_16x16x32_bf16 v[76:79], v[92:95], v[208:211], v[76:79]
	v_mfma_f32_16x16x32_bf16 v[136:139], v[112:115], v[160:163], v[136:139]
	v_mfma_f32_16x16x32_bf16 v[136:139], v[116:119], v[164:167], v[136:139]
	v_mfma_f32_16x16x32_bf16 v[120:123], v[112:115], v[188:191], v[120:123]
	v_mfma_f32_16x16x32_bf16 v[120:123], v[116:119], v[192:195], v[120:123]
	v_mfma_f32_16x16x32_bf16 v[96:99], v[112:115], v[196:199], v[96:99]
	v_mfma_f32_16x16x32_bf16 v[96:99], v[116:119], v[200:203], v[96:99]
	v_mfma_f32_16x16x32_bf16 v[72:75], v[112:115], v[204:207], v[72:75]
	v_mfma_f32_16x16x32_bf16 v[72:75], v[116:119], v[208:211], v[72:75]
	v_mfma_f32_16x16x32_bf16 v[132:135], v[144:147], v[160:163], v[132:135]
	v_mfma_f32_16x16x32_bf16 v[132:135], v[148:151], v[164:167], v[132:135]
	v_mfma_f32_16x16x32_bf16 v[108:111], v[144:147], v[188:191], v[108:111]
	v_mfma_f32_16x16x32_bf16 v[108:111], v[148:151], v[192:195], v[108:111]
	v_mfma_f32_16x16x32_bf16 v[84:87], v[144:147], v[196:199], v[84:87]
	v_mfma_f32_16x16x32_bf16 v[84:87], v[148:151], v[200:203], v[84:87]
	v_mfma_f32_16x16x32_bf16 v[68:71], v[144:147], v[204:207], v[68:71]
	v_mfma_f32_16x16x32_bf16 v[68:71], v[148:151], v[208:211], v[68:71]
	v_mfma_f32_16x16x32_bf16 v[128:131], v[152:155], v[160:163], v[128:131]
	v_mfma_f32_16x16x32_bf16 v[128:131], v[156:159], v[164:167], v[128:131]
	v_mfma_f32_16x16x32_bf16 v[104:107], v[152:155], v[188:191], v[104:107]
	v_mfma_f32_16x16x32_bf16 v[104:107], v[156:159], v[192:195], v[104:107]
	v_mfma_f32_16x16x32_bf16 v[80:83], v[152:155], v[196:199], v[80:83]
	v_mfma_f32_16x16x32_bf16 v[80:83], v[156:159], v[200:203], v[80:83]
	v_mfma_f32_16x16x32_bf16 v[64:67], v[152:155], v[204:207], v[64:67]
	v_mfma_f32_16x16x32_bf16 v[64:67], v[156:159], v[208:211], v[64:67]
	s_barrier
	s_add_u32 s20, s16, 0x40000
	s_addc_u32 s21, s17, 0
	s_add_i32 s63, s63, s18
	s_mov_b32 m0, s63
	ds_read_b128 v[160:163], v221 offset:49152
	ds_read_b128 v[164:167], v221 offset:50176
	ds_read_b128 v[188:191], v221 offset:51200
	ds_read_b128 v[192:195], v221 offset:52224
	ds_read_b128 v[196:199], v221 offset:53248
	ds_read_b128 v[200:203], v221 offset:54272
	ds_read_b128 v[204:207], v221 offset:55296
	ds_read_b128 v[208:211], v221 offset:56320
	global_load_lds_dwordx4 v170, s[20:21]
	s_add_i32 m0, s63, 0x2000
	s_add_u32 s16, s16, 0x44000
	global_load_lds_dwordx4 v174, s[20:21]
	s_addc_u32 s17, s17, 0
	s_add_i32 s20, s75, s18
	s_mov_b32 m0, s20
	s_nop 0
	global_load_lds_dwordx4 v170, s[16:17]
	s_add_i32 m0, s20, 0x2000
	s_nop 0
	global_load_lds_dwordx4 v174, s[16:17]
	s_mov_b32 m0, s64
	s_nop 0
	global_load_lds_dwordx4 v168, s[14:15]
	s_mov_b32 m0, s65
	s_nop 0
	global_load_lds_dwordx4 v172, s[14:15]
	s_waitcnt vmcnt(8)
	s_waitcnt lgkmcnt(0)
	s_barrier
	s_waitcnt lgkmcnt(0)
	v_mfma_f32_16x16x32_bf16 v[60:63], v[88:91], v[160:163], v[60:63]
	v_mfma_f32_16x16x32_bf16 v[60:63], v[92:95], v[164:167], v[60:63]
	v_mfma_f32_16x16x32_bf16 v[44:47], v[88:91], v[188:191], v[44:47]
	v_mfma_f32_16x16x32_bf16 v[44:47], v[92:95], v[192:195], v[44:47]
	v_mfma_f32_16x16x32_bf16 v[28:31], v[88:91], v[196:199], v[28:31]
	v_mfma_f32_16x16x32_bf16 v[28:31], v[92:95], v[200:203], v[28:31]
	v_mfma_f32_16x16x32_bf16 v[12:15], v[88:91], v[204:207], v[12:15]
	v_mfma_f32_16x16x32_bf16 v[12:15], v[92:95], v[208:211], v[12:15]
	v_mfma_f32_16x16x32_bf16 v[56:59], v[112:115], v[160:163], v[56:59]
	v_mfma_f32_16x16x32_bf16 v[56:59], v[116:119], v[164:167], v[56:59]
	v_mfma_f32_16x16x32_bf16 v[40:43], v[112:115], v[188:191], v[40:43]
	v_mfma_f32_16x16x32_bf16 v[40:43], v[116:119], v[192:195], v[40:43]
	v_mfma_f32_16x16x32_bf16 v[24:27], v[112:115], v[196:199], v[24:27]
	v_mfma_f32_16x16x32_bf16 v[24:27], v[116:119], v[200:203], v[24:27]
	v_mfma_f32_16x16x32_bf16 v[8:11], v[112:115], v[204:207], v[8:11]
	v_mfma_f32_16x16x32_bf16 v[8:11], v[116:119], v[208:211], v[8:11]
	v_mfma_f32_16x16x32_bf16 v[52:55], v[144:147], v[160:163], v[52:55]
	v_mfma_f32_16x16x32_bf16 v[52:55], v[148:151], v[164:167], v[52:55]
	v_mfma_f32_16x16x32_bf16 v[36:39], v[144:147], v[188:191], v[36:39]
	v_mfma_f32_16x16x32_bf16 v[36:39], v[148:151], v[192:195], v[36:39]
	v_mfma_f32_16x16x32_bf16 v[20:23], v[144:147], v[196:199], v[20:23]
	v_mfma_f32_16x16x32_bf16 v[20:23], v[148:151], v[200:203], v[20:23]
	v_mfma_f32_16x16x32_bf16 v[4:7], v[144:147], v[204:207], v[4:7]
	v_mfma_f32_16x16x32_bf16 v[4:7], v[148:151], v[208:211], v[4:7]
	v_mfma_f32_16x16x32_bf16 v[48:51], v[152:155], v[160:163], v[48:51]
	v_mfma_f32_16x16x32_bf16 v[48:51], v[156:159], v[164:167], v[48:51]
	v_mfma_f32_16x16x32_bf16 v[32:35], v[152:155], v[188:191], v[32:35]
	v_mfma_f32_16x16x32_bf16 v[32:35], v[156:159], v[192:195], v[32:35]
	v_mfma_f32_16x16x32_bf16 v[16:19], v[152:155], v[196:199], v[16:19]
	v_mfma_f32_16x16x32_bf16 v[16:19], v[156:159], v[200:203], v[16:19]
	v_mfma_f32_16x16x32_bf16 v[0:3], v[152:155], v[204:207], v[0:3]
	v_mfma_f32_16x16x32_bf16 v[0:3], v[156:159], v[208:211], v[0:3]
	s_barrier
	s_add_i32 s61, s61, 2
	s_add_u32 s22, s22, 0x80000
	s_addc_u32 s23, s23, 0
	s_add_u32 s12, s12, 0x400000
	s_addc_u32 s13, s13, 0
	s_cmp_gt_u32 s61, 13
	s_cbranch_scc0 .LBB0_952
	s_and_b64 vcc, exec, s[52:53]
	s_cbranch_vccz .LBB0_955
	s_barrier

; #define PG8_STAGE(bufoff, gbase, voff) do { _Pragma("unroll") for (int _i = 0; _i < 2; ++_i) \
;         __builtin_amdgcn_global_load_lds((const unsigned*)((const char*)(gbase) + (voff)[_i]), (LAS unsigned*)(lds + (bufoff) + ldsw + _i * 8192), 16, 0, 0); } while (0)
; #define PG8_LDA(dst, b, h) do { _Pragma("unroll") for (int m = 0; m < 4; ++m) _Pragma("unroll") for (int k = 0; k < 2; ++k) dst[m][k] = *(const LAS bf16x8*)(lds + PG8_SA(b, h) + aoff + m * 2048 + k * 1024); } while (0)
; #define PG8_LDB(dst, b, h) do { _Pragma("unroll") for (int n = 0; n < 2; ++n) _Pragma("unroll") for (int k = 0; k < 2; ++k) dst[n][k] = *(const LAS bf16x8*)(lds + PG8_SB(b, h) + boff + n * 2048 + k * 1024); } while (0)
; #define PG8_MMA(ai, bj, At, Bt) do { __builtin_amdgcn_s_setprio(1); _Pragma("unroll") for (int m = 0; m < 4; ++m) _Pragma("unroll") for (int n = 0; n < 2; ++n) _Pragma("unroll") for (int k = 0; k < 2; ++k) \
;         acc[ai][bj][m][n] = __builtin_amdgcn_mfma_f32_16x16x32_bf16(Bt[n][k], At[m][k], acc[ai][bj][m][n], 0, 0, 0); __builtin_amdgcn_s_setprio(0); } while (0)
; #define PG8_WAIT_V(n) asm volatile("s_waitcnt vmcnt(" #n ")" ::: "memory")
; #define PG8_WAIT_L(n) asm volatile("s_waitcnt lgkmcnt(" #n ")" ::: "memory")
; template <bool ALIGN_EPI, class Epi, class Sched>
; __device__ __forceinline__ void gemm_phase(LAS unsigned char* lds, const int lda, const int ldb, const int K, const Sched& S, const Epi& E, const size_t kstepA = (size_t)(BK * 2), const size_t kstepB = (size_t)(BK * 2)) {
;     ...
;         for (int t = 0; t < nt; t += 2) {
;             const bool last = (t == nt - 2);
;             const char* a1 = cA + (size_t)(t + 1) * kstepA;
;             const char* a2 = last ? nA : cA + (size_t)(t + 2) * kstepA; const char* b2 = last ? nB : cB + (size_t)(t + 2) * kstep;
;             const char* a3 = a2 + kstepA; const char* b3 = b2 + kstep;
;             PG8_LDB(B0, 0, 0); PG8_LDB(B1, 0, 1); PG8_SCHED; PG8_LDA(At, 0, 0); PG8_STAGE(PG8_SA(1, 1), a1 + hstepA, voffA);
;             PG8_WAIT_V(8); PG8_WAIT_L(0); PG8_BAR; PG8_MMA(0, 0, At, B0); PG8_MMA(0, 1, At, B1); PG8_BAR; PG8_SCHED;
;             PG8_LDA(At, 0, 1); PG8_STAGE(PG8_SB(0, 0), b2, voffB); PG8_STAGE(PG8_SB(0, 1), b2 + hstepB, voffB); PG8_STAGE(PG8_SA(0, 0), a2, voffA);
;             PG8_WAIT_V(8); PG8_WAIT_L(0); PG8_BAR; PG8_MMA(1, 0, At, B0); PG8_MMA(1, 1, At, B1); PG8_BAR; PG8_SCHED;
.LBB0_1044:
	ds_read_b128 v[148:151], v168
	ds_read_b128 v[172:175], v168 offset:1024
	ds_read_b128 v[176:179], v168 offset:2048
	ds_read_b128 v[180:183], v168 offset:3072
	ds_read_b128 v[186:189], v169
	ds_read_b128 v[190:193], v169 offset:1024
	ds_read_b128 v[194:197], v169 offset:2048
	ds_read_b128 v[198:201], v169 offset:3072
	s_add_u32 s48, s46, 0x1fc000
	s_addc_u32 s49, s47, 0
	s_cmp_eq_u32 s15, 28
	s_cselect_b32 s54, s22, s48
	s_cselect_b32 s55, s23, s49
	s_cselect_b32 s52, s44, s9
	s_cselect_b32 s53, s45, s13
	s_add_u32 s48, s54, 0x200000
	s_addc_u32 s49, s55, 0
	s_add_i32 m0, s29, 0xc000
	ds_read_b128 v[202:205], v170
	ds_read_b128 v[206:209], v170 offset:1024
	ds_read_b128 v[210:213], v170 offset:2048
	ds_read_b128 v[214:217], v170 offset:3072
	ds_read_b128 v[218:221], v170 offset:4096
	ds_read_b128 v[222:225], v170 offset:5120
	ds_read_b128 v[226:229], v170 offset:6144
	ds_read_b128 v[230:233], v170 offset:7168
	global_load_lds_dwordx4 v140, s[46:47]
	s_add_i32 m0, s29, 0xe000
	s_nop 0
	global_load_lds_dwordx4 v142, s[46:47]
	s_waitcnt vmcnt(8)
	s_waitcnt lgkmcnt(0)
	s_barrier
	s_waitcnt lgkmcnt(0)
	v_mfma_f32_16x16x32_bf16 v[124:127], v[148:151], v[202:205], v[124:127]
	v_mfma_f32_16x16x32_bf16 v[124:127], v[172:175], v[206:209], v[124:127]
	v_mfma_f32_16x16x32_bf16 v[108:111], v[148:151], v[210:213], v[108:111]
	v_mfma_f32_16x16x32_bf16 v[108:111], v[172:175], v[214:217], v[108:111]
	v_mfma_f32_16x16x32_bf16 v[92:95], v[148:151], v[218:221], v[92:95]
	v_mfma_f32_16x16x32_bf16 v[92:95], v[172:175], v[222:225], v[92:95]
	v_mfma_f32_16x16x32_bf16 v[76:79], v[148:151], v[226:229], v[76:79]
	v_mfma_f32_16x16x32_bf16 v[76:79], v[172:175], v[230:233], v[76:79]
	v_mfma_f32_16x16x32_bf16 v[120:123], v[176:179], v[202:205], v[120:123]
	v_mfma_f32_16x16x32_bf16 v[120:123], v[180:183], v[206:209], v[120:123]
	v_mfma_f32_16x16x32_bf16 v[104:107], v[176:179], v[210:213], v[104:107]
	v_mfma_f32_16x16x32_bf16 v[104:107], v[180:183], v[214:217], v[104:107]
	v_mfma_f32_16x16x32_bf16 v[88:91], v[176:179], v[218:221], v[88:91]
	v_mfma_f32_16x16x32_bf16 v[88:91], v[180:183], v[222:225], v[88:91]
	v_mfma_f32_16x16x32_bf16 v[72:75], v[176:179], v[226:229], v[72:75]
	v_mfma_f32_16x16x32_bf16 v[72:75], v[180:183], v[230:233], v[72:75]
	v_mfma_f32_16x16x32_bf16 v[116:119], v[186:189], v[202:205], v[116:119]
	v_mfma_f32_16x16x32_bf16 v[116:119], v[190:193], v[206:209], v[116:119]
	v_mfma_f32_16x16x32_bf16 v[100:103], v[186:189], v[210:213], v[100:103]
	v_mfma_f32_16x16x32_bf16 v[100:103], v[190:193], v[214:217], v[100:103]
	v_mfma_f32_16x16x32_bf16 v[84:87], v[186:189], v[218:221], v[84:87]
	v_mfma_f32_16x16x32_bf16 v[84:87], v[190:193], v[222:225], v[84:87]
	v_mfma_f32_16x16x32_bf16 v[68:71], v[186:189], v[226:229], v[68:71]
	v_mfma_f32_16x16x32_bf16 v[68:71], v[190:193], v[230:233], v[68:71]
	v_mfma_f32_16x16x32_bf16 v[112:115], v[194:197], v[202:205], v[112:115]
	v_mfma_f32_16x16x32_bf16 v[112:115], v[198:201], v[206:209], v[112:115]
	v_mfma_f32_16x16x32_bf16 v[96:99], v[194:197], v[210:213], v[96:99]
	v_mfma_f32_16x16x32_bf16 v[96:99], v[198:201], v[214:217], v[96:99]
	v_mfma_f32_16x16x32_bf16 v[80:83], v[194:197], v[218:221], v[80:83]
	v_mfma_f32_16x16x32_bf16 v[80:83], v[198:201], v[222:225], v[80:83]
	v_mfma_f32_16x16x32_bf16 v[64:67], v[194:197], v[226:229], v[64:67]
	v_mfma_f32_16x16x32_bf16 v[64:67], v[198:201], v[230:233], v[64:67]
	s_barrier
	s_add_i32 s61, s57, s19
	s_mov_b32 m0, s61
	ds_read_b128 v[202:205], v170 offset:16384
	ds_read_b128 v[206:209], v170 offset:17408
	ds_read_b128 v[210:213], v170 offset:18432
	ds_read_b128 v[214:217], v170 offset:19456
	ds_read_b128 v[218:221], v170 offset:20480
	ds_read_b128 v[222:225], v170 offset:21504
	ds_read_b128 v[226:229], v170 offset:22528
	ds_read_b128 v[230:233], v170 offset:23552
	global_load_lds_dwordx4 v130, s[52:53]
	s_add_i32 m0, s61, 0x2000
	s_add_u32 s62, s52, 0x4000
	s_addc_u32 s63, s53, 0
	s_add_i32 s61, s58, s19
	global_load_lds_dwordx4 v134, s[52:53]
	s_mov_b32 m0, s61
	s_nop 0
	global_load_lds_dwordx4 v130, s[62:63]
	s_add_i32 m0, s61, 0x2000
	s_nop 0
	global_load_lds_dwordx4 v134, s[62:63]
	s_mov_b32 m0, s29
	s_nop 0
	global_load_lds_dwordx4 v128, s[54:55]
	s_mov_b32 m0, s30
	s_nop 0
	global_load_lds_dwordx4 v132, s[54:55]
	s_waitcnt vmcnt(8)
	s_waitcnt lgkmcnt(0)
	s_barrier
	s_waitcnt lgkmcnt(0)
	v_mfma_f32_16x16x32_bf16 v[60:63], v[148:151], v[202:205], v[60:63]
	v_mfma_f32_16x16x32_bf16 v[60:63], v[172:175], v[206:209], v[60:63]
	v_mfma_f32_16x16x32_bf16 v[44:47], v[148:151], v[210:213], v[44:47]
	v_mfma_f32_16x16x32_bf16 v[44:47], v[172:175], v[214:217], v[44:47]
	v_mfma_f32_16x16x32_bf16 v[28:31], v[148:151], v[218:221], v[28:31]
	v_mfma_f32_16x16x32_bf16 v[28:31], v[172:175], v[222:225], v[28:31]
	v_mfma_f32_16x16x32_bf16 v[12:15], v[148:151], v[226:229], v[12:15]
	v_mfma_f32_16x16x32_bf16 v[12:15], v[172:175], v[230:233], v[12:15]
	v_mfma_f32_16x16x32_bf16 v[56:59], v[176:179], v[202:205], v[56:59]
	v_mfma_f32_16x16x32_bf16 v[56:59], v[180:183], v[206:209], v[56:59]
	v_mfma_f32_16x16x32_bf16 v[40:43], v[176:179], v[210:213], v[40:43]
	v_mfma_f32_16x16x32_bf16 v[40:43], v[180:183], v[214:217], v[40:43]
	v_mfma_f32_16x16x32_bf16 v[24:27], v[176:179], v[218:221], v[24:27]
	v_mfma_f32_16x16x32_bf16 v[24:27], v[180:183], v[222:225], v[24:27]
	v_mfma_f32_16x16x32_bf16 v[8:11], v[176:179], v[226:229], v[8:11]
	v_mfma_f32_16x16x32_bf16 v[8:11], v[180:183], v[230:233], v[8:11]
	v_mfma_f32_16x16x32_bf16 v[52:55], v[186:189], v[202:205], v[52:55]
	v_mfma_f32_16x16x32_bf16 v[52:55], v[190:193], v[206:209], v[52:55]
	v_mfma_f32_16x16x32_bf16 v[36:39], v[186:189], v[210:213], v[36:39]
	v_mfma_f32_16x16x32_bf16 v[36:39], v[190:193], v[214:217], v[36:39]
	v_mfma_f32_16x16x32_bf16 v[20:23], v[186:189], v[218:221], v[20:23]
	v_mfma_f32_16x16x32_bf16 v[20:23], v[190:193], v[222:225], v[20:23]
	v_mfma_f32_16x16x32_bf16 v[4:7], v[186:189], v[226:229], v[4:7]
	v_mfma_f32_16x16x32_bf16 v[4:7], v[190:193], v[230:233], v[4:7]
	v_mfma_f32_16x16x32_bf16 v[48:51], v[194:197], v[202:205], v[48:51]
	v_mfma_f32_16x16x32_bf16 v[48:51], v[198:201], v[206:209], v[48:51]
	v_mfma_f32_16x16x32_bf16 v[32:35], v[194:197], v[210:213], v[32:35]
	v_mfma_f32_16x16x32_bf16 v[32:35], v[198:201], v[214:217], v[32:35]
	v_mfma_f32_16x16x32_bf16 v[16:19], v[194:197], v[218:221], v[16:19]
	v_mfma_f32_16x16x32_bf16 v[16:19], v[198:201], v[222:225], v[16:19]
	v_mfma_f32_16x16x32_bf16 v[0:3], v[194:197], v[226:229], v[0:3]
	v_mfma_f32_16x16x32_bf16 v[0:3], v[198:201], v[230:233], v[0:3]
	s_barrier
; #define PG8_STAGE(bufoff, gbase, voff) do { _Pragma("unroll") for (int _i = 0; _i < 2; ++_i) \
;         __builtin_amdgcn_global_load_lds((const unsigned*)((const char*)(gbase) + (voff)[_i]), (LAS unsigned*)(lds + (bufoff) + ldsw + _i * 8192), 16, 0, 0); } while (0)
; #define PG8_LDA(dst, b, h) do { _Pragma("unroll") for (int m = 0; m < 4; ++m) _Pragma("unroll") for (int k = 0; k < 2; ++k) dst[m][k] = *(const LAS bf16x8*)(lds + PG8_SA(b, h) + aoff + m * 2048 + k * 1024); } while (0)
; #define PG8_LDB(dst, b, h) do { _Pragma("unroll") for (int n = 0; n < 2; ++n) _Pragma("unroll") for (int k = 0; k < 2; ++k) dst[n][k] = *(const LAS bf16x8*)(lds + PG8_SB(b, h) + boff + n * 2048 + k * 1024); } while (0)
; #define PG8_MMA(ai, bj, At, Bt) do { __builtin_amdgcn_s_setprio(1); _Pragma("unroll") for (int m = 0; m < 4; ++m) _Pragma("unroll") for (int n = 0; n < 2; ++n) _Pragma("unroll") for (int k = 0; k < 2; ++k) \
;         acc[ai][bj][m][n] = __builtin_amdgcn_mfma_f32_16x16x32_bf16(Bt[n][k], At[m][k], acc[ai][bj][m][n], 0, 0, 0); __builtin_amdgcn_s_setprio(0); } while (0)
; #define PG8_WAIT_V(n) asm volatile("s_waitcnt vmcnt(" #n ")" ::: "memory")
; #define PG8_WAIT_L(n) asm volatile("s_waitcnt lgkmcnt(" #n ")" ::: "memory")
; #define PG8_BAR __builtin_amdgcn_s_barrier()
; #define PG8_SCHED __builtin_amdgcn_sched_barrier(0)
; template <bool ALIGN_EPI, class Epi, class Sched>
; __device__ __forceinline__ void gemm_phase(LAS unsigned char* lds, const int lda, const int ldb, const int K, const Sched& S, const Epi& E, const size_t kstepA = (size_t)(BK * 2), const size_t kstepB = (size_t)(BK * 2)) {
;     ...
;             PG8_LDB(B0, 1, 0); PG8_LDB(B1, 1, 1); PG8_SCHED; PG8_LDA(At, 1, 0); PG8_STAGE(PG8_SA(0, 1), a2 + hstepA, voffA);
;             PG8_WAIT_V(8); PG8_WAIT_L(0); PG8_BAR; PG8_MMA(0, 0, At, B0); PG8_MMA(0, 1, At, B1); PG8_BAR; PG8_SCHED;
;             PG8_LDA(At, 1, 1); PG8_STAGE(PG8_SB(1, 0), b3, voffB); PG8_STAGE(PG8_SB(1, 1), b3 + hstepB, voffB); PG8_STAGE(PG8_SA(1, 0), a3, voffA);
;             PG8_WAIT_V(8); PG8_WAIT_L(0); PG8_BAR; PG8_MMA(1, 0, At, B0); PG8_MMA(1, 1, At, B1); PG8_BAR; PG8_SCHED;
;         }
	s_add_i32 s61, 0, 0x18000
	v_add_u32_e32 v136, s61, v152
	s_add_i32 s62, 0, 0x1c000
	ds_read_b128 v[148:151], v136
	ds_read_b128 v[172:175], v136 offset:1024
	ds_read_b128 v[176:179], v136 offset:2048
	ds_read_b128 v[180:183], v136 offset:3072
	v_add_u32_e32 v136, s62, v152
	ds_read_b128 v[186:189], v136
	ds_read_b128 v[190:193], v136 offset:1024
	ds_read_b128 v[194:197], v136 offset:2048
	ds_read_b128 v[198:201], v136 offset:3072
	s_add_u32 s54, s54, 0x4000
	s_addc_u32 s55, s55, 0
	s_mov_b32 m0, s31
	ds_read_b128 v[202:205], v170 offset:32768
	ds_read_b128 v[206:209], v170 offset:33792
	ds_read_b128 v[210:213], v170 offset:34816
	ds_read_b128 v[214:217], v170 offset:35840
	ds_read_b128 v[218:221], v170 offset:36864
	ds_read_b128 v[222:225], v170 offset:37888
	ds_read_b128 v[226:229], v170 offset:38912
	ds_read_b128 v[230:233], v170 offset:39936
	global_load_lds_dwordx4 v128, s[54:55]
	s_mov_b32 m0, s33
	s_nop 0
	global_load_lds_dwordx4 v132, s[54:55]
	s_waitcnt vmcnt(8)
	s_waitcnt lgkmcnt(0)
	s_barrier
	s_waitcnt lgkmcnt(0)
	v_mfma_f32_16x16x32_bf16 v[124:127], v[148:151], v[202:205], v[124:127]
	v_mfma_f32_16x16x32_bf16 v[124:127], v[172:175], v[206:209], v[124:127]
	v_mfma_f32_16x16x32_bf16 v[108:111], v[148:151], v[210:213], v[108:111]
	v_mfma_f32_16x16x32_bf16 v[108:111], v[172:175], v[214:217], v[108:111]
	v_mfma_f32_16x16x32_bf16 v[92:95], v[148:151], v[218:221], v[92:95]
	v_mfma_f32_16x16x32_bf16 v[92:95], v[172:175], v[222:225], v[92:95]
	v_mfma_f32_16x16x32_bf16 v[76:79], v[148:151], v[226:229], v[76:79]
	v_mfma_f32_16x16x32_bf16 v[76:79], v[172:175], v[230:233], v[76:79]
	v_mfma_f32_16x16x32_bf16 v[120:123], v[176:179], v[202:205], v[120:123]
	v_mfma_f32_16x16x32_bf16 v[120:123], v[180:183], v[206:209], v[120:123]
	v_mfma_f32_16x16x32_bf16 v[104:107], v[176:179], v[210:213], v[104:107]
	v_mfma_f32_16x16x32_bf16 v[104:107], v[180:183], v[214:217], v[104:107]
	v_mfma_f32_16x16x32_bf16 v[88:91], v[176:179], v[218:221], v[88:91]
	v_mfma_f32_16x16x32_bf16 v[88:91], v[180:183], v[222:225], v[88:91]
	v_mfma_f32_16x16x32_bf16 v[72:75], v[176:179], v[226:229], v[72:75]
	v_mfma_f32_16x16x32_bf16 v[72:75], v[180:183], v[230:233], v[72:75]
	v_mfma_f32_16x16x32_bf16 v[116:119], v[186:189], v[202:205], v[116:119]
	v_mfma_f32_16x16x32_bf16 v[116:119], v[190:193], v[206:209], v[116:119]
	v_mfma_f32_16x16x32_bf16 v[100:103], v[186:189], v[210:213], v[100:103]
	v_mfma_f32_16x16x32_bf16 v[100:103], v[190:193], v[214:217], v[100:103]
	v_mfma_f32_16x16x32_bf16 v[84:87], v[186:189], v[218:221], v[84:87]
	v_mfma_f32_16x16x32_bf16 v[84:87], v[190:193], v[222:225], v[84:87]
	v_mfma_f32_16x16x32_bf16 v[68:71], v[186:189], v[226:229], v[68:71]
	v_mfma_f32_16x16x32_bf16 v[68:71], v[190:193], v[230:233], v[68:71]
	v_mfma_f32_16x16x32_bf16 v[112:115], v[194:197], v[202:205], v[112:115]
	v_mfma_f32_16x16x32_bf16 v[112:115], v[198:201], v[206:209], v[112:115]
	v_mfma_f32_16x16x32_bf16 v[96:99], v[194:197], v[210:213], v[96:99]
	v_mfma_f32_16x16x32_bf16 v[96:99], v[198:201], v[214:217], v[96:99]
	v_mfma_f32_16x16x32_bf16 v[80:83], v[194:197], v[218:221], v[80:83]
	v_mfma_f32_16x16x32_bf16 v[80:83], v[198:201], v[222:225], v[80:83]
	v_mfma_f32_16x16x32_bf16 v[64:67], v[194:197], v[226:229], v[64:67]
	v_mfma_f32_16x16x32_bf16 v[64:67], v[198:201], v[230:233], v[64:67]
	s_barrier
	s_add_u32 s54, s52, 0x160000
	s_addc_u32 s55, s53, 0
	s_add_i32 s61, s61, s19
	s_mov_b32 m0, s61
	ds_read_b128 v[202:205], v170 offset:49152
	ds_read_b128 v[206:209], v170 offset:50176
	ds_read_b128 v[210:213], v170 offset:51200
	ds_read_b128 v[214:217], v170 offset:52224
	ds_read_b128 v[218:221], v170 offset:53248
	ds_read_b128 v[222:225], v170 offset:54272
	ds_read_b128 v[226:229], v170 offset:55296
	ds_read_b128 v[230:233], v170 offset:56320
	global_load_lds_dwordx4 v130, s[54:55]
	s_add_i32 m0, s61, 0x2000
	s_add_u32 s52, s52, 0x164000
	global_load_lds_dwordx4 v134, s[54:55]
	s_addc_u32 s53, s53, 0
	s_add_i32 s54, s62, s19
	s_mov_b32 m0, s54
	s_nop 0
	global_load_lds_dwordx4 v130, s[52:53]
	s_add_i32 m0, s54, 0x2000
	s_nop 0
	global_load_lds_dwordx4 v134, s[52:53]
	s_mov_b32 m0, s50
	s_nop 0
	global_load_lds_dwordx4 v128, s[48:49]
	s_mov_b32 m0, s51
	s_nop 0
	global_load_lds_dwordx4 v132, s[48:49]
	s_waitcnt vmcnt(8)
	s_waitcnt lgkmcnt(0)
	s_barrier
	s_waitcnt lgkmcnt(0)
	v_mfma_f32_16x16x32_bf16 v[60:63], v[148:151], v[202:205], v[60:63]
	v_mfma_f32_16x16x32_bf16 v[60:63], v[172:175], v[206:209], v[60:63]
	v_mfma_f32_16x16x32_bf16 v[44:47], v[148:151], v[210:213], v[44:47]
	v_mfma_f32_16x16x32_bf16 v[44:47], v[172:175], v[214:217], v[44:47]
	v_mfma_f32_16x16x32_bf16 v[28:31], v[148:151], v[218:221], v[28:31]
	v_mfma_f32_16x16x32_bf16 v[28:31], v[172:175], v[222:225], v[28:31]
	v_mfma_f32_16x16x32_bf16 v[12:15], v[148:151], v[226:229], v[12:15]
	v_mfma_f32_16x16x32_bf16 v[12:15], v[172:175], v[230:233], v[12:15]
	v_mfma_f32_16x16x32_bf16 v[56:59], v[176:179], v[202:205], v[56:59]
	v_mfma_f32_16x16x32_bf16 v[56:59], v[180:183], v[206:209], v[56:59]
	v_mfma_f32_16x16x32_bf16 v[40:43], v[176:179], v[210:213], v[40:43]
	v_mfma_f32_16x16x32_bf16 v[40:43], v[180:183], v[214:217], v[40:43]
	v_mfma_f32_16x16x32_bf16 v[24:27], v[176:179], v[218:221], v[24:27]
	v_mfma_f32_16x16x32_bf16 v[24:27], v[180:183], v[222:225], v[24:27]
	v_mfma_f32_16x16x32_bf16 v[8:11], v[176:179], v[226:229], v[8:11]
	v_mfma_f32_16x16x32_bf16 v[8:11], v[180:183], v[230:233], v[8:11]
	v_mfma_f32_16x16x32_bf16 v[52:55], v[186:189], v[202:205], v[52:55]
	v_mfma_f32_16x16x32_bf16 v[52:55], v[190:193], v[206:209], v[52:55]
	v_mfma_f32_16x16x32_bf16 v[36:39], v[186:189], v[210:213], v[36:39]
	v_mfma_f32_16x16x32_bf16 v[36:39], v[190:193], v[214:217], v[36:39]
	v_mfma_f32_16x16x32_bf16 v[20:23], v[186:189], v[218:221], v[20:23]
	v_mfma_f32_16x16x32_bf16 v[20:23], v[190:193], v[222:225], v[20:23]
	v_mfma_f32_16x16x32_bf16 v[4:7], v[186:189], v[226:229], v[4:7]
	v_mfma_f32_16x16x32_bf16 v[4:7], v[190:193], v[230:233], v[4:7]
	v_mfma_f32_16x16x32_bf16 v[48:51], v[194:197], v[202:205], v[48:51]
	v_mfma_f32_16x16x32_bf16 v[48:51], v[198:201], v[206:209], v[48:51]
	v_mfma_f32_16x16x32_bf16 v[32:35], v[194:197], v[210:213], v[32:35]
	v_mfma_f32_16x16x32_bf16 v[32:35], v[198:201], v[214:217], v[32:35]
	v_mfma_f32_16x16x32_bf16 v[16:19], v[194:197], v[218:221], v[16:19]
	v_mfma_f32_16x16x32_bf16 v[16:19], v[198:201], v[222:225], v[16:19]
	v_mfma_f32_16x16x32_bf16 v[0:3], v[194:197], v[226:229], v[0:3]
	v_mfma_f32_16x16x32_bf16 v[0:3], v[198:201], v[230:233], v[0:3]
	s_barrier
	s_add_i32 s15, s15, 2
	s_add_u32 s9, s9, 0x2c0000
	s_addc_u32 s13, s13, 0
	s_add_u32 s46, s46, 0x400000
	s_addc_u32 s47, s47, 0
	s_cmp_gt_u32 s15, 29
	s_cbranch_scc0 .LBB0_1044
	s_and_b64 vcc, exec, s[10:11]
	s_cbranch_vccz .LBB0_1047
	s_barrier

; #define PG8_STAGE(bufoff, gbase, voff) do { _Pragma("unroll") for (int _i = 0; _i < 2; ++_i) \
;         __builtin_amdgcn_global_load_lds((const unsigned*)((const char*)(gbase) + (voff)[_i]), (LAS unsigned*)(lds + (bufoff) + ldsw + _i * 8192), 16, 0, 0); } while (0)
; #define PG8_LDA(dst, b, h) do { _Pragma("unroll") for (int m = 0; m < 4; ++m) _Pragma("unroll") for (int k = 0; k < 2; ++k) dst[m][k] = *(const LAS bf16x8*)(lds + PG8_SA(b, h) + aoff + m * 2048 + k * 1024); } while (0)
; #define PG8_LDB(dst, b, h) do { _Pragma("unroll") for (int n = 0; n < 2; ++n) _Pragma("unroll") for (int k = 0; k < 2; ++k) dst[n][k] = *(const LAS bf16x8*)(lds + PG8_SB(b, h) + boff + n * 2048 + k * 1024); } while (0)
; #define PG8_MMA(ai, bj, At, Bt) do { __builtin_amdgcn_s_setprio(1); _Pragma("unroll") for (int m = 0; m < 4; ++m) _Pragma("unroll") for (int n = 0; n < 2; ++n) _Pragma("unroll") for (int k = 0; k < 2; ++k) \
;         acc[ai][bj][m][n] = __builtin_amdgcn_mfma_f32_16x16x32_bf16(Bt[n][k], At[m][k], acc[ai][bj][m][n], 0, 0, 0); __builtin_amdgcn_s_setprio(0); } while (0)
; #define PG8_WAIT_V(n) asm volatile("s_waitcnt vmcnt(" #n ")" ::: "memory")
; #define PG8_WAIT_L(n) asm volatile("s_waitcnt lgkmcnt(" #n ")" ::: "memory")
; template <bool ALIGN_EPI, class Epi, class Sched>
; __device__ __forceinline__ void gemm_phase(LAS unsigned char* lds, const int lda, const int ldb, const int K, const Sched& S, const Epi& E, const size_t kstepA = (size_t)(BK * 2), const size_t kstepB = (size_t)(BK * 2)) {
;     ...
;         for (int t = 0; t < nt; t += 2) {
;             const bool last = (t == nt - 2);
;             const char* a1 = cA + (size_t)(t + 1) * kstepA;
;             const char* a2 = last ? nA : cA + (size_t)(t + 2) * kstepA; const char* b2 = last ? nB : cB + (size_t)(t + 2) * kstep;
;             const char* a3 = a2 + kstepA; const char* b3 = b2 + kstep;
;             PG8_LDB(B0, 0, 0); PG8_LDB(B1, 0, 1); PG8_SCHED; PG8_LDA(At, 0, 0); PG8_STAGE(PG8_SA(1, 1), a1 + hstepA, voffA);
;             PG8_WAIT_V(8); PG8_WAIT_L(0); PG8_BAR; PG8_MMA(0, 0, At, B0); PG8_MMA(0, 1, At, B1); PG8_BAR; PG8_SCHED;
;             PG8_LDA(At, 0, 1); PG8_STAGE(PG8_SB(0, 0), b2, voffB); PG8_STAGE(PG8_SB(0, 1), b2 + hstepB, voffB); PG8_STAGE(PG8_SA(0, 0), a2, voffA);
;             PG8_WAIT_V(8); PG8_WAIT_L(0); PG8_BAR; PG8_MMA(1, 0, At, B0); PG8_MMA(1, 1, At, B1); PG8_BAR; PG8_SCHED;
.LBB0_1154:
	ds_read_b128 v[80:83], v219
	ds_read_b128 v[84:87], v219 offset:1024
	ds_read_b128 v[104:107], v219 offset:2048
	ds_read_b128 v[108:111], v219 offset:3072
	ds_read_b128 v[144:147], v220
	ds_read_b128 v[148:151], v220 offset:1024
	ds_read_b128 v[152:155], v220 offset:2048
	ds_read_b128 v[156:159], v220 offset:3072
	s_add_u32 s12, s10, 0x1fc000
	s_addc_u32 s13, s11, 0
	s_cmpk_eq_i32 s67, 0x54
	s_cselect_b32 s16, s0, s12
	s_cselect_b32 s17, s1, s13
	s_cselect_b32 s14, s8, s57
	s_cselect_b32 s15, s9, s59
	s_add_u32 s12, s16, 0x200000
	s_addc_u32 s13, s17, 0
	s_add_i32 m0, s19, 0xc000
	ds_read_b128 v[160:163], v221
	ds_read_b128 v[164:167], v221 offset:1024
	ds_read_b128 v[188:191], v221 offset:2048
	ds_read_b128 v[192:195], v221 offset:3072
	ds_read_b128 v[196:199], v221 offset:4096
	ds_read_b128 v[200:203], v221 offset:5120
	ds_read_b128 v[204:207], v221 offset:6144
	ds_read_b128 v[208:211], v221 offset:7168
	global_load_lds_dwordx4 v178, s[10:11]
	s_add_i32 m0, s19, 0xe000
	s_nop 0
	global_load_lds_dwordx4 v180, s[10:11]
	s_waitcnt vmcnt(8)
	s_waitcnt lgkmcnt(0)
	s_barrier
	s_waitcnt lgkmcnt(0)
	v_mfma_f32_16x16x32_bf16 v[140:143], v[80:83], v[160:163], v[140:143]
	v_mfma_f32_16x16x32_bf16 v[140:143], v[84:87], v[164:167], v[140:143]
	v_mfma_f32_16x16x32_bf16 v[124:127], v[80:83], v[188:191], v[124:127]
	v_mfma_f32_16x16x32_bf16 v[124:127], v[84:87], v[192:195], v[124:127]
	v_mfma_f32_16x16x32_bf16 v[100:103], v[80:83], v[196:199], v[100:103]
	v_mfma_f32_16x16x32_bf16 v[100:103], v[84:87], v[200:203], v[100:103]
	v_mfma_f32_16x16x32_bf16 v[76:79], v[80:83], v[204:207], v[76:79]
	v_mfma_f32_16x16x32_bf16 v[76:79], v[84:87], v[208:211], v[76:79]
	v_mfma_f32_16x16x32_bf16 v[136:139], v[104:107], v[160:163], v[136:139]
	v_mfma_f32_16x16x32_bf16 v[136:139], v[108:111], v[164:167], v[136:139]
	v_mfma_f32_16x16x32_bf16 v[120:123], v[104:107], v[188:191], v[120:123]
	v_mfma_f32_16x16x32_bf16 v[120:123], v[108:111], v[192:195], v[120:123]
	v_mfma_f32_16x16x32_bf16 v[96:99], v[104:107], v[196:199], v[96:99]
	v_mfma_f32_16x16x32_bf16 v[96:99], v[108:111], v[200:203], v[96:99]
	v_mfma_f32_16x16x32_bf16 v[72:75], v[104:107], v[204:207], v[72:75]
	v_mfma_f32_16x16x32_bf16 v[72:75], v[108:111], v[208:211], v[72:75]
	v_mfma_f32_16x16x32_bf16 v[132:135], v[144:147], v[160:163], v[132:135]
	v_mfma_f32_16x16x32_bf16 v[132:135], v[148:151], v[164:167], v[132:135]
	v_mfma_f32_16x16x32_bf16 v[116:119], v[144:147], v[188:191], v[116:119]
	v_mfma_f32_16x16x32_bf16 v[116:119], v[148:151], v[192:195], v[116:119]
	v_mfma_f32_16x16x32_bf16 v[92:95], v[144:147], v[196:199], v[92:95]
	v_mfma_f32_16x16x32_bf16 v[92:95], v[148:151], v[200:203], v[92:95]
	v_mfma_f32_16x16x32_bf16 v[68:71], v[144:147], v[204:207], v[68:71]
	v_mfma_f32_16x16x32_bf16 v[68:71], v[148:151], v[208:211], v[68:71]
	v_mfma_f32_16x16x32_bf16 v[128:131], v[152:155], v[160:163], v[128:131]
	v_mfma_f32_16x16x32_bf16 v[128:131], v[156:159], v[164:167], v[128:131]
	v_mfma_f32_16x16x32_bf16 v[112:115], v[152:155], v[188:191], v[112:115]
	v_mfma_f32_16x16x32_bf16 v[112:115], v[156:159], v[192:195], v[112:115]
	v_mfma_f32_16x16x32_bf16 v[88:91], v[152:155], v[196:199], v[88:91]
	v_mfma_f32_16x16x32_bf16 v[88:91], v[156:159], v[200:203], v[88:91]
	v_mfma_f32_16x16x32_bf16 v[64:67], v[152:155], v[204:207], v[64:67]
	v_mfma_f32_16x16x32_bf16 v[64:67], v[156:159], v[208:211], v[64:67]
	s_barrier
	s_add_i32 s68, s51, s18
	s_mov_b32 m0, s68
	ds_read_b128 v[160:163], v221 offset:16384
	ds_read_b128 v[164:167], v221 offset:17408
	ds_read_b128 v[188:191], v221 offset:18432
	ds_read_b128 v[192:195], v221 offset:19456
	ds_read_b128 v[196:199], v221 offset:20480
	ds_read_b128 v[200:203], v221 offset:21504
	ds_read_b128 v[204:207], v221 offset:22528
	ds_read_b128 v[208:211], v221 offset:23552
	global_load_lds_dwordx4 v170, s[14:15]
	s_add_i32 m0, s68, 0x2000
	s_add_u32 s68, s14, 0x4000
	s_addc_u32 s69, s15, 0
	s_add_i32 s70, s64, s18
	global_load_lds_dwordx4 v174, s[14:15]
	s_mov_b32 m0, s70
	s_nop 0
	global_load_lds_dwordx4 v170, s[68:69]
	s_add_i32 m0, s70, 0x2000
	s_nop 0
	global_load_lds_dwordx4 v174, s[68:69]
	s_mov_b32 m0, s19
	s_nop 0
	global_load_lds_dwordx4 v168, s[16:17]
	s_mov_b32 m0, s29
	s_nop 0
	global_load_lds_dwordx4 v172, s[16:17]
	s_waitcnt vmcnt(8)
	s_waitcnt lgkmcnt(0)
	s_barrier
	s_waitcnt lgkmcnt(0)
	v_mfma_f32_16x16x32_bf16 v[60:63], v[80:83], v[160:163], v[60:63]
	v_mfma_f32_16x16x32_bf16 v[60:63], v[84:87], v[164:167], v[60:63]
	v_mfma_f32_16x16x32_bf16 v[44:47], v[80:83], v[188:191], v[44:47]
	v_mfma_f32_16x16x32_bf16 v[44:47], v[84:87], v[192:195], v[44:47]
	v_mfma_f32_16x16x32_bf16 v[28:31], v[80:83], v[196:199], v[28:31]
	v_mfma_f32_16x16x32_bf16 v[28:31], v[84:87], v[200:203], v[28:31]
	v_mfma_f32_16x16x32_bf16 v[12:15], v[80:83], v[204:207], v[12:15]
	v_mfma_f32_16x16x32_bf16 v[12:15], v[84:87], v[208:211], v[12:15]
	v_mfma_f32_16x16x32_bf16 v[56:59], v[104:107], v[160:163], v[56:59]
	v_mfma_f32_16x16x32_bf16 v[56:59], v[108:111], v[164:167], v[56:59]
	v_mfma_f32_16x16x32_bf16 v[40:43], v[104:107], v[188:191], v[40:43]
	v_mfma_f32_16x16x32_bf16 v[40:43], v[108:111], v[192:195], v[40:43]
	v_mfma_f32_16x16x32_bf16 v[24:27], v[104:107], v[196:199], v[24:27]
	v_mfma_f32_16x16x32_bf16 v[24:27], v[108:111], v[200:203], v[24:27]
	v_mfma_f32_16x16x32_bf16 v[8:11], v[104:107], v[204:207], v[8:11]
	v_mfma_f32_16x16x32_bf16 v[8:11], v[108:111], v[208:211], v[8:11]
	v_mfma_f32_16x16x32_bf16 v[52:55], v[144:147], v[160:163], v[52:55]
	v_mfma_f32_16x16x32_bf16 v[52:55], v[148:151], v[164:167], v[52:55]
	v_mfma_f32_16x16x32_bf16 v[36:39], v[144:147], v[188:191], v[36:39]
	v_mfma_f32_16x16x32_bf16 v[36:39], v[148:151], v[192:195], v[36:39]
	v_mfma_f32_16x16x32_bf16 v[20:23], v[144:147], v[196:199], v[20:23]
	v_mfma_f32_16x16x32_bf16 v[20:23], v[148:151], v[200:203], v[20:23]
	v_mfma_f32_16x16x32_bf16 v[4:7], v[144:147], v[204:207], v[4:7]
	v_mfma_f32_16x16x32_bf16 v[4:7], v[148:151], v[208:211], v[4:7]
	v_mfma_f32_16x16x32_bf16 v[48:51], v[152:155], v[160:163], v[48:51]
	v_mfma_f32_16x16x32_bf16 v[48:51], v[156:159], v[164:167], v[48:51]
	v_mfma_f32_16x16x32_bf16 v[32:35], v[152:155], v[188:191], v[32:35]
	v_mfma_f32_16x16x32_bf16 v[32:35], v[156:159], v[192:195], v[32:35]
	v_mfma_f32_16x16x32_bf16 v[16:19], v[152:155], v[196:199], v[16:19]
	v_mfma_f32_16x16x32_bf16 v[16:19], v[156:159], v[200:203], v[16:19]
	v_mfma_f32_16x16x32_bf16 v[0:3], v[152:155], v[204:207], v[0:3]
	v_mfma_f32_16x16x32_bf16 v[0:3], v[156:159], v[208:211], v[0:3]
	s_barrier
; #define PG8_STAGE(bufoff, gbase, voff) do { _Pragma("unroll") for (int _i = 0; _i < 2; ++_i) \
;         __builtin_amdgcn_global_load_lds((const unsigned*)((const char*)(gbase) + (voff)[_i]), (LAS unsigned*)(lds + (bufoff) + ldsw + _i * 8192), 16, 0, 0); } while (0)
; #define PG8_LDA(dst, b, h) do { _Pragma("unroll") for (int m = 0; m < 4; ++m) _Pragma("unroll") for (int k = 0; k < 2; ++k) dst[m][k] = *(const LAS bf16x8*)(lds + PG8_SA(b, h) + aoff + m * 2048 + k * 1024); } while (0)
; #define PG8_LDB(dst, b, h) do { _Pragma("unroll") for (int n = 0; n < 2; ++n) _Pragma("unroll") for (int k = 0; k < 2; ++k) dst[n][k] = *(const LAS bf16x8*)(lds + PG8_SB(b, h) + boff + n * 2048 + k * 1024); } while (0)
; #define PG8_MMA(ai, bj, At, Bt) do { __builtin_amdgcn_s_setprio(1); _Pragma("unroll") for (int m = 0; m < 4; ++m) _Pragma("unroll") for (int n = 0; n < 2; ++n) _Pragma("unroll") for (int k = 0; k < 2; ++k) \
;         acc[ai][bj][m][n] = __builtin_amdgcn_mfma_f32_16x16x32_bf16(Bt[n][k], At[m][k], acc[ai][bj][m][n], 0, 0, 0); __builtin_amdgcn_s_setprio(0); } while (0)
; #define PG8_WAIT_V(n) asm volatile("s_waitcnt vmcnt(" #n ")" ::: "memory")
; #define PG8_WAIT_L(n) asm volatile("s_waitcnt lgkmcnt(" #n ")" ::: "memory")
; #define PG8_BAR __builtin_amdgcn_s_barrier()
; #define PG8_SCHED __builtin_amdgcn_sched_barrier(0)
; template <bool ALIGN_EPI, class Epi, class Sched>
; __device__ __forceinline__ void gemm_phase(LAS unsigned char* lds, const int lda, const int ldb, const int K, const Sched& S, const Epi& E, const size_t kstepA = (size_t)(BK * 2), const size_t kstepB = (size_t)(BK * 2)) {
;     ...
;             PG8_LDB(B0, 1, 0); PG8_LDB(B1, 1, 1); PG8_SCHED; PG8_LDA(At, 1, 0); PG8_STAGE(PG8_SA(0, 1), a2 + hstepA, voffA);
;             PG8_WAIT_V(8); PG8_WAIT_L(0); PG8_BAR; PG8_MMA(0, 0, At, B0); PG8_MMA(0, 1, At, B1); PG8_BAR; PG8_SCHED;
;             PG8_LDA(At, 1, 1); PG8_STAGE(PG8_SB(1, 0), b3, voffB); PG8_STAGE(PG8_SB(1, 1), b3 + hstepB, voffB); PG8_STAGE(PG8_SA(1, 0), a3, voffA);
;             PG8_WAIT_V(8); PG8_WAIT_L(0); PG8_BAR; PG8_MMA(1, 0, At, B0); PG8_MMA(1, 1, At, B1); PG8_BAR; PG8_SCHED;
;         }
;         if constexpr (ALIGN_EPI) { if (wr == 0) PG8_BAR; }
	s_add_i32 s68, 0, 0x18000
	s_add_i32 s69, 0, 0x1c000
	v_add_u32_e32 v108, s68, v218
	v_add_u32_e32 v156, s69, v218
	ds_read_b128 v[80:83], v108
	ds_read_b128 v[84:87], v108 offset:1024
	ds_read_b128 v[104:107], v108 offset:2048
	ds_read_b128 v[108:111], v108 offset:3072
	ds_read_b128 v[144:147], v156
	ds_read_b128 v[148:151], v156 offset:1024
	ds_read_b128 v[152:155], v156 offset:2048
	ds_read_b128 v[156:159], v156 offset:3072
	s_add_u32 s16, s16, 0x4000
	s_addc_u32 s17, s17, 0
	s_mov_b32 m0, s30
	ds_read_b128 v[160:163], v221 offset:32768
	ds_read_b128 v[164:167], v221 offset:33792
	ds_read_b128 v[188:191], v221 offset:34816
	ds_read_b128 v[192:195], v221 offset:35840
	ds_read_b128 v[196:199], v221 offset:36864
	ds_read_b128 v[200:203], v221 offset:37888
	ds_read_b128 v[204:207], v221 offset:38912
	ds_read_b128 v[208:211], v221 offset:39936
	global_load_lds_dwordx4 v168, s[16:17]
	s_mov_b32 m0, s31
	s_nop 0
	global_load_lds_dwordx4 v172, s[16:17]
	s_waitcnt vmcnt(8)
	s_waitcnt lgkmcnt(0)
	s_barrier
	s_waitcnt lgkmcnt(0)
	v_mfma_f32_16x16x32_bf16 v[140:143], v[80:83], v[160:163], v[140:143]
	v_mfma_f32_16x16x32_bf16 v[140:143], v[84:87], v[164:167], v[140:143]
	v_mfma_f32_16x16x32_bf16 v[124:127], v[80:83], v[188:191], v[124:127]
	v_mfma_f32_16x16x32_bf16 v[124:127], v[84:87], v[192:195], v[124:127]
	v_mfma_f32_16x16x32_bf16 v[100:103], v[80:83], v[196:199], v[100:103]
	v_mfma_f32_16x16x32_bf16 v[100:103], v[84:87], v[200:203], v[100:103]
	v_mfma_f32_16x16x32_bf16 v[76:79], v[80:83], v[204:207], v[76:79]
	v_mfma_f32_16x16x32_bf16 v[76:79], v[84:87], v[208:211], v[76:79]
	v_mfma_f32_16x16x32_bf16 v[136:139], v[104:107], v[160:163], v[136:139]
	v_mfma_f32_16x16x32_bf16 v[136:139], v[108:111], v[164:167], v[136:139]
	v_mfma_f32_16x16x32_bf16 v[120:123], v[104:107], v[188:191], v[120:123]
	v_mfma_f32_16x16x32_bf16 v[120:123], v[108:111], v[192:195], v[120:123]
	v_mfma_f32_16x16x32_bf16 v[96:99], v[104:107], v[196:199], v[96:99]
	v_mfma_f32_16x16x32_bf16 v[96:99], v[108:111], v[200:203], v[96:99]
	v_mfma_f32_16x16x32_bf16 v[72:75], v[104:107], v[204:207], v[72:75]
	v_mfma_f32_16x16x32_bf16 v[72:75], v[108:111], v[208:211], v[72:75]
	v_mfma_f32_16x16x32_bf16 v[132:135], v[144:147], v[160:163], v[132:135]
	v_mfma_f32_16x16x32_bf16 v[132:135], v[148:151], v[164:167], v[132:135]
	v_mfma_f32_16x16x32_bf16 v[116:119], v[144:147], v[188:191], v[116:119]
	v_mfma_f32_16x16x32_bf16 v[116:119], v[148:151], v[192:195], v[116:119]
	v_mfma_f32_16x16x32_bf16 v[92:95], v[144:147], v[196:199], v[92:95]
	v_mfma_f32_16x16x32_bf16 v[92:95], v[148:151], v[200:203], v[92:95]
	v_mfma_f32_16x16x32_bf16 v[68:71], v[144:147], v[204:207], v[68:71]
	v_mfma_f32_16x16x32_bf16 v[68:71], v[148:151], v[208:211], v[68:71]
	v_mfma_f32_16x16x32_bf16 v[128:131], v[152:155], v[160:163], v[128:131]
	v_mfma_f32_16x16x32_bf16 v[128:131], v[156:159], v[164:167], v[128:131]
	v_mfma_f32_16x16x32_bf16 v[112:115], v[152:155], v[188:191], v[112:115]
	v_mfma_f32_16x16x32_bf16 v[112:115], v[156:159], v[192:195], v[112:115]
	v_mfma_f32_16x16x32_bf16 v[88:91], v[152:155], v[196:199], v[88:91]
	v_mfma_f32_16x16x32_bf16 v[88:91], v[156:159], v[200:203], v[88:91]
	v_mfma_f32_16x16x32_bf16 v[64:67], v[152:155], v[204:207], v[64:67]
	v_mfma_f32_16x16x32_bf16 v[64:67], v[156:159], v[208:211], v[64:67]
	s_barrier
	s_add_u32 s16, s14, 0x40000
	s_addc_u32 s17, s15, 0
	s_add_i32 s68, s68, s18
	s_mov_b32 m0, s68
	ds_read_b128 v[160:163], v221 offset:49152
	ds_read_b128 v[164:167], v221 offset:50176
	ds_read_b128 v[188:191], v221 offset:51200
	ds_read_b128 v[192:195], v221 offset:52224
	ds_read_b128 v[196:199], v221 offset:53248
	ds_read_b128 v[200:203], v221 offset:54272
	ds_read_b128 v[204:207], v221 offset:55296
	ds_read_b128 v[208:211], v221 offset:56320
	global_load_lds_dwordx4 v170, s[16:17]
	s_add_i32 m0, s68, 0x2000
	s_add_u32 s14, s14, 0x44000
	global_load_lds_dwordx4 v174, s[16:17]
	s_addc_u32 s15, s15, 0
	s_add_i32 s16, s69, s18
	s_mov_b32 m0, s16
	s_nop 0
	global_load_lds_dwordx4 v170, s[14:15]
	s_add_i32 m0, s16, 0x2000
	s_nop 0
	global_load_lds_dwordx4 v174, s[14:15]
	s_mov_b32 m0, s43
	s_nop 0
	global_load_lds_dwordx4 v168, s[12:13]
	s_mov_b32 m0, s50
	s_nop 0
	global_load_lds_dwordx4 v172, s[12:13]
	s_waitcnt vmcnt(8)
	s_waitcnt lgkmcnt(0)
	s_barrier
	s_waitcnt lgkmcnt(0)
	v_mfma_f32_16x16x32_bf16 v[60:63], v[80:83], v[160:163], v[60:63]
	v_mfma_f32_16x16x32_bf16 v[60:63], v[84:87], v[164:167], v[60:63]
	v_mfma_f32_16x16x32_bf16 v[44:47], v[80:83], v[188:191], v[44:47]
	v_mfma_f32_16x16x32_bf16 v[44:47], v[84:87], v[192:195], v[44:47]
	v_mfma_f32_16x16x32_bf16 v[28:31], v[80:83], v[196:199], v[28:31]
	v_mfma_f32_16x16x32_bf16 v[28:31], v[84:87], v[200:203], v[28:31]
	v_mfma_f32_16x16x32_bf16 v[12:15], v[80:83], v[204:207], v[12:15]
	v_mfma_f32_16x16x32_bf16 v[12:15], v[84:87], v[208:211], v[12:15]
	v_mfma_f32_16x16x32_bf16 v[56:59], v[104:107], v[160:163], v[56:59]
	v_mfma_f32_16x16x32_bf16 v[56:59], v[108:111], v[164:167], v[56:59]
	v_mfma_f32_16x16x32_bf16 v[40:43], v[104:107], v[188:191], v[40:43]
	v_mfma_f32_16x16x32_bf16 v[40:43], v[108:111], v[192:195], v[40:43]
	v_mfma_f32_16x16x32_bf16 v[24:27], v[104:107], v[196:199], v[24:27]
	v_mfma_f32_16x16x32_bf16 v[24:27], v[108:111], v[200:203], v[24:27]
	v_mfma_f32_16x16x32_bf16 v[8:11], v[104:107], v[204:207], v[8:11]
	v_mfma_f32_16x16x32_bf16 v[8:11], v[108:111], v[208:211], v[8:11]
	v_mfma_f32_16x16x32_bf16 v[52:55], v[144:147], v[160:163], v[52:55]
	v_mfma_f32_16x16x32_bf16 v[52:55], v[148:151], v[164:167], v[52:55]
	v_mfma_f32_16x16x32_bf16 v[36:39], v[144:147], v[188:191], v[36:39]
	v_mfma_f32_16x16x32_bf16 v[36:39], v[148:151], v[192:195], v[36:39]
	v_mfma_f32_16x16x32_bf16 v[20:23], v[144:147], v[196:199], v[20:23]
	v_mfma_f32_16x16x32_bf16 v[20:23], v[148:151], v[200:203], v[20:23]
	v_mfma_f32_16x16x32_bf16 v[4:7], v[144:147], v[204:207], v[4:7]
	v_mfma_f32_16x16x32_bf16 v[4:7], v[148:151], v[208:211], v[4:7]
	v_mfma_f32_16x16x32_bf16 v[48:51], v[152:155], v[160:163], v[48:51]
	v_mfma_f32_16x16x32_bf16 v[48:51], v[156:159], v[164:167], v[48:51]
	v_mfma_f32_16x16x32_bf16 v[32:35], v[152:155], v[188:191], v[32:35]
	v_mfma_f32_16x16x32_bf16 v[32:35], v[156:159], v[192:195], v[32:35]
	v_mfma_f32_16x16x32_bf16 v[16:19], v[152:155], v[196:199], v[16:19]
	v_mfma_f32_16x16x32_bf16 v[16:19], v[156:159], v[200:203], v[16:19]
	v_mfma_f32_16x16x32_bf16 v[0:3], v[152:155], v[204:207], v[0:3]
	v_mfma_f32_16x16x32_bf16 v[0:3], v[156:159], v[208:211], v[0:3]
	s_barrier
	s_add_i32 s67, s67, 2
	s_add_u32 s57, s57, 0x80000
	s_addc_u32 s59, s59, 0
	s_add_u32 s10, s10, 0x400000
	s_addc_u32 s11, s11, 0
	s_cmpk_gt_u32 s67, 0x55
	s_cbranch_scc0 .LBB0_1154
	s_and_b64 vcc, exec, s[46:47]
	s_cbranch_vccz .LBB0_1157
	s_barrier
